# attention gathers: xnack-replay pads between back-to-back gathers dropped (72), 18 leftover offset moves folded
# speedup vs baseline: 1.0006x; 1.0006x over previous
; #define LAS __attribute__((address_space(3)))
; #define ATT_KISSUE(slot_, hg_) do { v2i kx_[4]; \
;             _Pragma("unroll") for (int i = 0; i < 4; ++i) kx_[i] = *(const LAS v2i*)(idl2 + rg * 64 + 16 * i + 2 * (hg_)); \
;             _Pragma("unroll") for (int j = 0; j < 2; ++j) _Pragma("unroll") for (int i = 0; i < 4; ++i) kf[slot_][j][i] = *(const v4u*)(kvb + (size_t)kx_[i][j] * KVD); \
;             ATT_FENCE(); } while (0)
; DI void attn_worker(unsigned char* ws, LAS unsigned char* lds, LAS unsigned* qctr, int wave) {
;     ...
;         f32x4 s[16]; v4u kf[3][2][4];
;     ...
;         ATT_KISSUE(0, 0); ATT_KISSUE(1, 1);
; #pragma unroll
;         for (int hg = 0; hg < 8; ++hg) {
;             if (hg + 2 < 8) ATT_KISSUE((hg + 2) % 3, hg + 2);
; #pragma unroll
;             for (int j = 0; j < 2; ++j) {
; #pragma unroll
;                 for (int i = 0; i < 4; ++i) *(LAS v4u*)(stg + j * 4096 + woff[i]) = kf[hg % 3][j][i];
;                 bf16x8 ka[4];
; #pragma unroll
;                 for (int ks = 0; ks < 4; ++ks) ka[ks] = *(const LAS bf16x8*)(stg + j * 4096 + roff[ks]);
;                 f32x4 a = {0.f, 0.f, 0.f, 0.f};
; #pragma unroll
;                 for (int ks = 0; ks < 4; ++ks) a = __builtin_amdgcn_mfma_f32_16x16x32_bf16(ka[ks], qf[ks], a, 0, 0, 0);
;                 s[2 * hg + j] = a; }
.LBB0_2280:
	ds_read2_b64 v[16:19], v182 offset0:128 offset1:136
	ds_read2_b64 v[20:23], v182 offset0:144 offset1:152
	s_waitcnt lgkmcnt(1)
	v_lshl_add_u32 v28, v16, 10, v252
	v_lshl_add_u32 v30, v18, 10, v252
	global_load_dwordx4 v[24:27], v28, s[98:99]
	global_load_dwordx4 v[60:63], v30, s[98:99]
	s_waitcnt lgkmcnt(0)
	v_lshl_add_u32 v28, v20, 10, v252
	v_lshl_add_u32 v30, v22, 10, v252
	global_load_dwordx4 v[72:75], v28, s[98:99]
	global_load_dwordx4 v[84:87], v30, s[98:99]
	v_lshl_add_u32 v28, v17, 10, v252
	v_lshl_add_u32 v30, v19, 10, v252
	global_load_dwordx4 v[16:19], v28, s[98:99]
	global_load_dwordx4 v[88:91], v30, s[98:99]
	v_lshl_add_u32 v28, v21, 10, v252
	v_mov_b32_e32 v20, v28
	v_lshl_add_u32 v28, v23, 10, v252
	global_load_dwordx4 v[20:23], v20, s[98:99]
	global_load_dwordx4 v[96:99], v28, s[98:99]
	ds_read2_b64 v[28:31], v182 offset0:129 offset1:137
	ds_read2_b64 v[48:51], v182 offset0:145 offset1:153
	s_waitcnt lgkmcnt(1)
	v_lshl_add_u32 v32, v28, 10, v252
	s_waitcnt lgkmcnt(0)
	v_lshl_add_u32 v40, v48, 10, v252
	v_lshl_add_u32 v36, v30, 10, v252
	global_load_dwordx4 v[32:35], v32, s[98:99]
	global_load_dwordx4 v[36:39], v36, s[98:99]
	v_lshl_add_u32 v44, v50, 10, v252
	global_load_dwordx4 v[40:43], v40, s[98:99]
	global_load_dwordx4 v[80:83], v44, s[98:99]
	v_lshl_add_u32 v44, v29, 10, v252
	v_mov_b32_e32 v28, v44
	v_lshl_add_u32 v44, v31, 10, v252
	v_mov_b32_e32 v30, v44
	global_load_dwordx4 v[44:47], v28, s[98:99]
	global_load_dwordx4 v[68:71], v30, s[98:99]
	v_lshl_add_u32 v28, v49, 10, v252
	v_lshl_add_u32 v30, v51, 10, v252
	global_load_dwordx4 v[100:103], v28, s[98:99]
	global_load_dwordx4 v[108:111], v30, s[98:99]
	ds_read2_b64 v[52:55], v182 offset0:130 offset1:138
	ds_read2_b64 v[92:95], v182 offset0:146 offset1:154
	s_waitcnt lgkmcnt(1)
	v_lshl_add_u32 v28, v52, 10, v252
	s_waitcnt lgkmcnt(0)
	v_lshl_add_u32 v56, v92, 10, v252
	v_lshl_add_u32 v58, v94, 10, v252
	v_lshl_add_u32 v48, v54, 10, v252
	global_load_dwordx4 v[28:31], v28, s[98:99]
	global_load_dwordx4 v[48:51], v48, s[98:99]
	global_load_dwordx4 v[64:67], v56, s[98:99]
	global_load_dwordx4 v[76:79], v58, s[98:99]
	v_lshl_add_u32 v56, v53, 10, v252
	v_lshl_add_u32 v104, v93, 10, v252
	v_mov_b32_e32 v52, v56
	v_lshl_add_u32 v56, v55, 10, v252
	v_mov_b32_e32 v92, v104
	v_lshl_add_u32 v104, v95, 10, v252
	global_load_dwordx4 v[52:55], v52, s[98:99]
	global_load_dwordx4 v[56:59], v56, s[98:99]
	global_load_dwordx4 v[92:95], v92, s[98:99]
	global_load_dwordx4 v[104:107], v104, s[98:99]
	s_waitcnt vmcnt(23)
	ds_write_b128 v227, v[24:27] offset:6144
	s_waitcnt vmcnt(22)
	ds_write_b128 v228, v[60:63] offset:6144
	s_waitcnt vmcnt(21)
	ds_write_b128 v229, v[72:75] offset:6144
	s_waitcnt vmcnt(20)
	ds_write_b128 v230, v[84:87] offset:6144
	ds_read_b128 v[24:27], v231 offset:6144
	ds_read_b128 v[60:63], v232 offset:6144
	s_waitcnt lgkmcnt(1)
	v_mfma_f32_16x16x32_bf16 v[24:27], v[24:27], v[4:7], 0
	s_waitcnt lgkmcnt(0)
	v_mfma_f32_16x16x32_bf16 v[24:27], v[60:63], v[0:3], v[24:27]
	ds_read_b128 v[60:63], v233 offset:6144
	ds_read_b128 v[72:75], v234 offset:6144
	s_waitcnt vmcnt(19)
	ds_write_b128 v227, v[16:19] offset:10240
	s_waitcnt vmcnt(18)
	ds_write_b128 v228, v[88:91] offset:10240
	s_waitcnt vmcnt(17)
	ds_write_b128 v229, v[20:23] offset:10240
	s_waitcnt vmcnt(16)
	ds_write_b128 v230, v[96:99] offset:10240
	ds_read_b128 v[16:19], v231 offset:10240
	ds_read_b128 v[20:23], v232 offset:10240
	s_waitcnt lgkmcnt(7)
	v_mfma_f32_16x16x32_bf16 v[24:27], v[60:63], v[12:15], v[24:27]
	ds_read_b128 v[60:63], v233 offset:10240
	s_waitcnt lgkmcnt(2)
	v_mfma_f32_16x16x32_bf16 v[16:19], v[16:19], v[4:7], 0
	v_mfma_f32_16x16x32_bf16 v[24:27], v[72:75], v[8:11], v[24:27]
	ds_read2_b64 v[72:75], v182 offset0:131 offset1:139
	ds_read_b128 v[88:91], v234 offset:10240
	ds_read2_b64 v[116:119], v182 offset0:147 offset1:155
	s_waitcnt lgkmcnt(0)
	v_mfma_f32_16x16x32_bf16 v[16:19], v[20:23], v[0:3], v[16:19]
	v_lshl_add_u32 v120, v117, 10, v252
	v_mfma_f32_16x16x32_bf16 v[112:115], v[60:63], v[12:15], v[16:19]
	v_lshl_add_u32 v60, v116, 10, v252
	s_nop 2
	v_lshl_add_u32 v16, v72, 10, v252
	v_lshl_add_u32 v62, v118, 10, v252
	v_lshl_add_u32 v20, v74, 10, v252
	global_load_dwordx4 v[16:19], v16, s[98:99]
	global_load_dwordx4 v[20:23], v20, s[98:99]
	global_load_dwordx4 v[84:87], v60, s[98:99]
	global_load_dwordx4 v[96:99], v62, s[98:99]
	v_lshl_add_u32 v60, v73, 10, v252
	v_mov_b32_e32 v116, v120
	v_lshl_add_u32 v120, v119, 10, v252
	v_lshl_add_u32 v72, v75, 10, v252
	global_load_dwordx4 v[60:63], v60, s[98:99]
	global_load_dwordx4 v[72:75], v72, s[98:99]
	global_load_dwordx4 v[116:119], v116, s[98:99]
	global_load_dwordx4 v[124:127], v120, s[98:99]
	s_waitcnt vmcnt(23)
	ds_write_b128 v227, v[32:35] offset:6144
	s_waitcnt vmcnt(22)
	ds_write_b128 v228, v[36:39] offset:6144
	s_waitcnt vmcnt(21)
	ds_write_b128 v229, v[40:43] offset:6144
	s_waitcnt vmcnt(20)
	ds_write_b128 v230, v[80:83] offset:6144
	ds_read_b128 v[32:35], v231 offset:6144
	ds_read_b128 v[36:39], v232 offset:6144
	s_waitcnt lgkmcnt(1)
	v_mfma_f32_16x16x32_bf16 v[32:35], v[32:35], v[4:7], 0
	s_waitcnt lgkmcnt(0)
	v_mfma_f32_16x16x32_bf16 v[32:35], v[36:39], v[0:3], v[32:35]
	ds_read_b128 v[36:39], v233 offset:6144
	ds_read_b128 v[80:83], v234 offset:6144
	s_waitcnt vmcnt(19)
	ds_write_b128 v227, v[44:47] offset:10240
	s_waitcnt vmcnt(18)
	ds_write_b128 v228, v[68:71] offset:10240
	s_waitcnt vmcnt(17)
	ds_write_b128 v229, v[100:103] offset:10240
	s_waitcnt vmcnt(16)
	ds_write_b128 v230, v[108:111] offset:10240
	ds_read_b128 v[68:71], v233 offset:10240
	s_waitcnt lgkmcnt(6)
; #define LAS __attribute__((address_space(3)))
; #define ATT_KISSUE(slot_, hg_) do { v2i kx_[4]; \
;             _Pragma("unroll") for (int i = 0; i < 4; ++i) kx_[i] = *(const LAS v2i*)(idl2 + rg * 64 + 16 * i + 2 * (hg_)); \
;             _Pragma("unroll") for (int j = 0; j < 2; ++j) _Pragma("unroll") for (int i = 0; i < 4; ++i) kf[slot_][j][i] = *(const v4u*)(kvb + (size_t)kx_[i][j] * KVD); \
;             ATT_FENCE(); } while (0)
; DI void attn_worker(unsigned char* ws, LAS unsigned char* lds, LAS unsigned* qctr, int wave) {
;     ...
;         f32x4 s[16]; v4u kf[3][2][4];
;     ...
;         ATT_KISSUE(0, 0); ATT_KISSUE(1, 1);
; #pragma unroll
;         for (int hg = 0; hg < 8; ++hg) {
;             if (hg + 2 < 8) ATT_KISSUE((hg + 2) % 3, hg + 2);
; #pragma unroll
;             for (int j = 0; j < 2; ++j) {
; #pragma unroll
;                 for (int i = 0; i < 4; ++i) *(LAS v4u*)(stg + j * 4096 + woff[i]) = kf[hg % 3][j][i];
;                 bf16x8 ka[4];
; #pragma unroll
;                 for (int ks = 0; ks < 4; ++ks) ka[ks] = *(const LAS bf16x8*)(stg + j * 4096 + roff[ks]);
;                 f32x4 a = {0.f, 0.f, 0.f, 0.f};
; #pragma unroll
;                 for (int ks = 0; ks < 4; ++ks) a = __builtin_amdgcn_mfma_f32_16x16x32_bf16(ka[ks], qf[ks], a, 0, 0, 0);
;                 s[2 * hg + j] = a; }
	v_mfma_f32_16x16x32_bf16 v[32:35], v[36:39], v[12:15], v[32:35]
	ds_read_b128 v[36:39], v231 offset:10240
	s_waitcnt lgkmcnt(6)
	v_mfma_f32_16x16x32_bf16 v[44:47], v[80:83], v[8:11], v[32:35]
	s_nop 4
	ds_read_b128 v[32:35], v232 offset:10240
	s_waitcnt lgkmcnt(1)
	v_mfma_f32_16x16x32_bf16 v[36:39], v[36:39], v[4:7], 0
	ds_read2_b64 v[80:83], v182 offset0:132 offset1:140
	ds_read_b128 v[108:111], v234 offset:10240
	ds_read2_b64 v[120:123], v182 offset0:148 offset1:156
	s_waitcnt lgkmcnt(0)
	v_mfma_f32_16x16x32_bf16 v[32:35], v[32:35], v[0:3], v[36:39]
	v_lshl_add_u32 v128, v121, 10, v252
	v_mfma_f32_16x16x32_bf16 v[40:43], v[88:91], v[8:11], v[112:115]
	v_mfma_f32_16x16x32_bf16 v[112:115], v[68:71], v[12:15], v[32:35]
	v_lshl_add_u32 v68, v120, 10, v252
	s_nop 1
	v_lshl_add_u32 v32, v80, 10, v252
	v_lshl_add_u32 v70, v122, 10, v252
	v_lshl_add_u32 v36, v82, 10, v252
	global_load_dwordx4 v[32:35], v32, s[98:99]
	global_load_dwordx4 v[36:39], v36, s[98:99]
	global_load_dwordx4 v[88:91], v68, s[98:99]
	global_load_dwordx4 v[100:103], v70, s[98:99]
	v_lshl_add_u32 v68, v81, 10, v252
	v_mov_b32_e32 v120, v128
	v_lshl_add_u32 v128, v123, 10, v252
	v_lshl_add_u32 v80, v83, 10, v252
	global_load_dwordx4 v[68:71], v68, s[98:99]
	global_load_dwordx4 v[80:83], v80, s[98:99]
	global_load_dwordx4 v[120:123], v120, s[98:99]
	global_load_dwordx4 v[128:131], v128, s[98:99]
	s_waitcnt vmcnt(23)
	ds_write_b128 v227, v[28:31] offset:6144
	s_waitcnt vmcnt(22)
	ds_write_b128 v228, v[48:51] offset:6144
	s_waitcnt vmcnt(21)
	ds_write_b128 v229, v[64:67] offset:6144
	s_waitcnt vmcnt(20)
	ds_write_b128 v230, v[76:79] offset:6144
	ds_read_b128 v[28:31], v231 offset:6144
	ds_read_b128 v[48:51], v232 offset:6144
	s_waitcnt lgkmcnt(1)
	v_mfma_f32_16x16x32_bf16 v[28:31], v[28:31], v[4:7], 0
	s_waitcnt lgkmcnt(0)
	v_mfma_f32_16x16x32_bf16 v[28:31], v[48:51], v[0:3], v[28:31]
	ds_read_b128 v[48:51], v233 offset:6144
	ds_read_b128 v[64:67], v234 offset:6144
	s_waitcnt vmcnt(19)
	ds_write_b128 v227, v[52:55] offset:10240
	s_waitcnt vmcnt(18)
	ds_write_b128 v228, v[56:59] offset:10240
	s_waitcnt vmcnt(17)
	ds_write_b128 v229, v[92:95] offset:10240
	s_waitcnt vmcnt(16)
	ds_write_b128 v230, v[104:107] offset:10240
	ds_read_b128 v[52:55], v232 offset:10240
	s_waitcnt lgkmcnt(6)
	v_mfma_f32_16x16x32_bf16 v[28:31], v[48:51], v[12:15], v[28:31]
	ds_read_b128 v[48:51], v231 offset:10240
	ds_read_b128 v[56:59], v233 offset:10240
	s_waitcnt lgkmcnt(1)
	v_mfma_f32_16x16x32_bf16 v[48:51], v[48:51], v[4:7], 0
	v_mfma_f32_16x16x32_bf16 v[76:79], v[108:111], v[8:11], v[112:115]
	v_mfma_f32_16x16x32_bf16 v[28:31], v[64:67], v[8:11], v[28:31]
	ds_read2_b64 v[64:67], v182 offset0:133 offset1:141
	ds_read_b128 v[144:147], v234 offset:10240
	ds_read2_b64 v[108:111], v182 offset0:149 offset1:157
	s_waitcnt lgkmcnt(0)
	v_mfma_f32_16x16x32_bf16 v[48:51], v[52:55], v[0:3], v[48:51]
	v_lshl_add_u32 v112, v109, 10, v252
	v_mfma_f32_16x16x32_bf16 v[148:151], v[56:59], v[12:15], v[48:51]
	v_lshl_add_u32 v56, v108, 10, v252
	s_nop 2
	v_lshl_add_u32 v48, v64, 10, v252
	v_lshl_add_u32 v58, v110, 10, v252
	v_lshl_add_u32 v52, v66, 10, v252
	global_load_dwordx4 v[48:51], v48, s[98:99]
	global_load_dwordx4 v[52:55], v52, s[98:99]
	global_load_dwordx4 v[92:95], v56, s[98:99]
	global_load_dwordx4 v[104:107], v58, s[98:99]
	v_lshl_add_u32 v56, v65, 10, v252
	v_mov_b32_e32 v108, v112
	v_lshl_add_u32 v112, v111, 10, v252
	v_lshl_add_u32 v64, v67, 10, v252
	global_load_dwordx4 v[56:59], v56, s[98:99]
	global_load_dwordx4 v[64:67], v64, s[98:99]
	global_load_dwordx4 v[108:111], v108, s[98:99]
	global_load_dwordx4 v[112:115], v112, s[98:99]
	s_waitcnt vmcnt(23)
	ds_write_b128 v227, v[16:19] offset:6144
	s_waitcnt vmcnt(22)
	ds_write_b128 v228, v[20:23] offset:6144
	s_waitcnt vmcnt(21)
	ds_write_b128 v229, v[84:87] offset:6144
	s_waitcnt vmcnt(20)
	ds_write_b128 v230, v[96:99] offset:6144
	ds_read_b128 v[20:23], v231 offset:6144
	ds_read_b128 v[84:87], v232 offset:6144
	s_waitcnt lgkmcnt(1)
	v_mfma_f32_16x16x32_bf16 v[20:23], v[20:23], v[4:7], 0
	s_waitcnt lgkmcnt(0)
	v_mfma_f32_16x16x32_bf16 v[20:23], v[84:87], v[0:3], v[20:23]
	ds_read_b128 v[84:87], v233 offset:6144
	ds_read_b128 v[96:99], v234 offset:6144
	s_waitcnt vmcnt(19)
	ds_write_b128 v227, v[60:63] offset:10240
	s_waitcnt vmcnt(18)
	ds_write_b128 v228, v[72:75] offset:10240
	s_waitcnt vmcnt(17)
	ds_write_b128 v229, v[116:119] offset:10240
	s_waitcnt vmcnt(16)
	ds_write_b128 v230, v[124:127] offset:10240
	ds_read_b128 v[60:63], v231 offset:10240
	ds_read_b128 v[72:75], v232 offset:10240
	s_waitcnt lgkmcnt(7)
	v_mfma_f32_16x16x32_bf16 v[20:23], v[84:87], v[12:15], v[20:23]
	ds_read_b128 v[84:87], v233 offset:10240
	s_waitcnt lgkmcnt(7)
	v_mfma_f32_16x16x32_bf16 v[20:23], v[96:99], v[8:11], v[20:23]
	ds_read2_b64 v[96:99], v182 offset0:134 offset1:142
	ds_read_b128 v[116:119], v234 offset:10240
	ds_read2_b64 v[124:127], v182 offset0:150 offset1:158
	s_waitcnt lgkmcnt(2)
	v_mfma_f32_16x16x32_bf16 v[60:63], v[60:63], v[4:7], 0
	v_lshl_add_u32 v152, v97, 10, v252
	s_waitcnt lgkmcnt(0)
	v_lshl_add_u32 v156, v125, 10, v252
	v_mfma_f32_16x16x32_bf16 v[60:63], v[72:75], v[0:3], v[60:63]
	v_lshl_add_u32 v72, v96, 10, v252
	v_mfma_f32_16x16x32_bf16 v[16:19], v[144:147], v[8:11], v[148:151]
	v_lshl_add_u32 v74, v98, 10, v252
	v_lshl_add_u32 v144, v124, 10, v252
	v_lshl_add_u32 v146, v126, 10, v252
	v_mov_b32_e32 v96, v152
	v_lshl_add_u32 v152, v99, 10, v252
	v_mov_b32_e32 v124, v156
	v_lshl_add_u32 v156, v127, 10, v252
	v_mfma_f32_16x16x32_bf16 v[60:63], v[84:87], v[12:15], v[60:63]
	v_mov_b32_e32 v84, v74
	v_mov_b32_e32 v148, v146
	global_load_dwordx4 v[72:75], v72, s[98:99]
	global_load_dwordx4 v[84:87], v84, s[98:99]
	global_load_dwordx4 v[144:147], v144, s[98:99]
	global_load_dwordx4 v[148:151], v148, s[98:99]
	global_load_dwordx4 v[96:99], v96, s[98:99]
	global_load_dwordx4 v[152:155], v152, s[98:99]
	global_load_dwordx4 v[124:127], v124, s[98:99]
	global_load_dwordx4 v[156:159], v156, s[98:99]
	s_waitcnt vmcnt(23)
; #define LAS __attribute__((address_space(3)))
; #define ATT_KISSUE(slot_, hg_) do { v2i kx_[4]; \
;             _Pragma("unroll") for (int i = 0; i < 4; ++i) kx_[i] = *(const LAS v2i*)(idl2 + rg * 64 + 16 * i + 2 * (hg_)); \
;             _Pragma("unroll") for (int j = 0; j < 2; ++j) _Pragma("unroll") for (int i = 0; i < 4; ++i) kf[slot_][j][i] = *(const v4u*)(kvb + (size_t)kx_[i][j] * KVD); \
;             ATT_FENCE(); } while (0)
; DI void attn_worker(unsigned char* ws, LAS unsigned char* lds, LAS unsigned* qctr, int wave) {
;     ...
;         f32x4 s[16]; v4u kf[3][2][4];
;     ...
;         ATT_KISSUE(0, 0); ATT_KISSUE(1, 1);
; #pragma unroll
;         for (int hg = 0; hg < 8; ++hg) {
;             if (hg + 2 < 8) ATT_KISSUE((hg + 2) % 3, hg + 2);
; #pragma unroll
;             for (int j = 0; j < 2; ++j) {
; #pragma unroll
;                 for (int i = 0; i < 4; ++i) *(LAS v4u*)(stg + j * 4096 + woff[i]) = kf[hg % 3][j][i];
;                 bf16x8 ka[4];
; #pragma unroll
;                 for (int ks = 0; ks < 4; ++ks) ka[ks] = *(const LAS bf16x8*)(stg + j * 4096 + roff[ks]);
;                 f32x4 a = {0.f, 0.f, 0.f, 0.f};
; #pragma unroll
;                 for (int ks = 0; ks < 4; ++ks) a = __builtin_amdgcn_mfma_f32_16x16x32_bf16(ka[ks], qf[ks], a, 0, 0, 0);
;                 s[2 * hg + j] = a; }
;         }
	ds_write_b128 v227, v[32:35] offset:6144
	s_waitcnt vmcnt(22)
	ds_write_b128 v228, v[36:39] offset:6144
	s_waitcnt vmcnt(21)
	ds_write_b128 v229, v[88:91] offset:6144
	s_waitcnt vmcnt(20)
	ds_write_b128 v230, v[100:103] offset:6144
	ds_read_b128 v[32:35], v231 offset:6144
	v_mfma_f32_16x16x32_bf16 v[36:39], v[116:119], v[8:11], v[60:63]
	s_nop 2
	ds_read_b128 v[60:63], v232 offset:6144
	s_waitcnt lgkmcnt(1)
	v_mfma_f32_16x16x32_bf16 v[32:35], v[32:35], v[4:7], 0
	s_waitcnt lgkmcnt(0)
	v_mfma_f32_16x16x32_bf16 v[32:35], v[60:63], v[0:3], v[32:35]
	ds_read_b128 v[60:63], v233 offset:6144
	ds_read_b128 v[88:91], v234 offset:6144
	s_waitcnt vmcnt(19)
	ds_write_b128 v227, v[68:71] offset:10240
	s_waitcnt vmcnt(18)
	ds_write_b128 v228, v[80:83] offset:10240
	s_waitcnt vmcnt(17)
	ds_write_b128 v229, v[120:123] offset:10240
	s_waitcnt vmcnt(16)
	ds_write_b128 v230, v[128:131] offset:10240
	ds_read_b128 v[68:71], v232 offset:10240
	s_waitcnt lgkmcnt(6)
	v_mfma_f32_16x16x32_bf16 v[32:35], v[60:63], v[12:15], v[32:35]
	ds_read_b128 v[60:63], v231 offset:10240
	ds_read_b128 v[80:83], v233 offset:10240
	s_waitcnt lgkmcnt(1)
	v_mfma_f32_16x16x32_bf16 v[60:63], v[60:63], v[4:7], 0
	v_mfma_f32_16x16x32_bf16 v[60:63], v[68:71], v[0:3], v[60:63]
	v_mfma_f32_16x16x32_bf16 v[32:35], v[88:91], v[8:11], v[32:35]
	ds_read2_b64 v[68:71], v182 offset0:135 offset1:143
	ds_read_b128 v[88:91], v234 offset:10240
	s_waitcnt lgkmcnt(1)
	v_mfma_f32_16x16x32_bf16 v[60:63], v[80:83], v[12:15], v[60:63]
	ds_read2_b64 v[80:83], v182 offset0:151 offset1:159
	v_lshl_add_u32 v100, v68, 10, v252
	s_waitcnt lgkmcnt(0)
	v_lshl_add_u32 v120, v80, 10, v252
	v_lshl_add_u32 v116, v70, 10, v252
	v_lshl_add_u32 v128, v82, 10, v252
	global_load_dwordx4 v[100:103], v100, s[98:99]
	global_load_dwordx4 v[116:119], v116, s[98:99]
	global_load_dwordx4 v[120:123], v120, s[98:99]
	global_load_dwordx4 v[128:131], v128, s[98:99]
	v_lshl_add_u32 v160, v69, 10, v252
	v_lshl_add_u32 v164, v81, 10, v252
	v_mov_b32_e32 v68, v160
	v_lshl_add_u32 v160, v71, 10, v252
	v_mov_b32_e32 v80, v164
	v_lshl_add_u32 v164, v83, 10, v252
	global_load_dwordx4 v[68:71], v68, s[98:99]
	global_load_dwordx4 v[160:163], v160, s[98:99]
	global_load_dwordx4 v[80:83], v80, s[98:99]
	global_load_dwordx4 v[164:167], v164, s[98:99]
	s_waitcnt vmcnt(23)
	ds_write_b128 v227, v[48:51] offset:6144
	s_waitcnt vmcnt(22)
	ds_write_b128 v228, v[52:55] offset:6144
	s_waitcnt vmcnt(21)
	ds_write_b128 v229, v[92:95] offset:6144
	s_waitcnt vmcnt(20)
	ds_write_b128 v230, v[104:107] offset:6144
	ds_read_b128 v[48:51], v231 offset:6144
	ds_read_b128 v[52:55], v232 offset:6144
	s_waitcnt lgkmcnt(1)
	v_mfma_f32_16x16x32_bf16 v[48:51], v[48:51], v[4:7], 0
	v_mfma_f32_16x16x32_bf16 v[60:63], v[88:91], v[8:11], v[60:63]
	s_waitcnt lgkmcnt(0)
	v_mfma_f32_16x16x32_bf16 v[48:51], v[52:55], v[0:3], v[48:51]
	ds_read_b128 v[52:55], v233 offset:6144
	ds_read_b128 v[88:91], v234 offset:6144
	s_waitcnt vmcnt(19)
	ds_write_b128 v227, v[56:59] offset:10240
	s_waitcnt vmcnt(18)
	ds_write_b128 v228, v[64:67] offset:10240
	s_waitcnt vmcnt(17)
	ds_write_b128 v229, v[108:111] offset:10240
	s_waitcnt vmcnt(16)
	ds_write_b128 v230, v[112:115] offset:10240
	ds_read_b128 v[56:59], v231 offset:10240
	s_waitcnt lgkmcnt(6)
	v_mfma_f32_16x16x32_bf16 v[48:51], v[52:55], v[12:15], v[48:51]
	s_waitcnt lgkmcnt(5)
	v_mfma_f32_16x16x32_bf16 v[52:55], v[88:91], v[8:11], v[48:51]
	s_nop 5
	ds_read_b128 v[48:51], v232 offset:10240
	s_waitcnt lgkmcnt(1)
	v_mfma_f32_16x16x32_bf16 v[56:59], v[56:59], v[4:7], 0
	s_waitcnt lgkmcnt(0)
	v_mfma_f32_16x16x32_bf16 v[48:51], v[48:51], v[0:3], v[56:59]
	s_nop 5
	ds_read_b128 v[56:59], v233 offset:10240
	ds_read_b128 v[64:67], v234 offset:10240
	s_waitcnt vmcnt(15)
	ds_write_b128 v227, v[72:75] offset:6144
	s_waitcnt vmcnt(14)
	ds_write_b128 v228, v[84:87] offset:6144
	s_waitcnt vmcnt(13)
	ds_write_b128 v229, v[144:147] offset:6144
	s_waitcnt vmcnt(12)
	ds_write_b128 v230, v[148:151] offset:6144
	s_waitcnt lgkmcnt(5)
	v_mfma_f32_16x16x32_bf16 v[48:51], v[56:59], v[12:15], v[48:51]
	ds_read_b128 v[56:59], v231 offset:6144
	s_waitcnt lgkmcnt(5)
	v_mfma_f32_16x16x32_bf16 v[48:51], v[64:67], v[8:11], v[48:51]
	ds_read_b128 v[64:67], v232 offset:6144
	s_waitcnt lgkmcnt(1)
	v_mfma_f32_16x16x32_bf16 v[56:59], v[56:59], v[4:7], 0
	s_waitcnt lgkmcnt(0)
	v_mfma_f32_16x16x32_bf16 v[56:59], v[64:67], v[0:3], v[56:59]
	ds_read_b128 v[64:67], v233 offset:6144
	ds_read_b128 v[72:75], v234 offset:6144
	s_waitcnt vmcnt(11)
	ds_write_b128 v227, v[96:99] offset:10240
	s_waitcnt vmcnt(10)
	ds_write_b128 v228, v[152:155] offset:10240
	s_waitcnt vmcnt(9)
	ds_write_b128 v229, v[124:127] offset:10240
	s_waitcnt vmcnt(8)
	ds_write_b128 v230, v[156:159] offset:10240
	s_waitcnt lgkmcnt(5)
	v_mfma_f32_16x16x32_bf16 v[56:59], v[64:67], v[12:15], v[56:59]
	ds_read_b128 v[64:67], v231 offset:10240
	s_waitcnt lgkmcnt(5)
	v_mfma_f32_16x16x32_bf16 v[56:59], v[72:75], v[8:11], v[56:59]
	ds_read_b128 v[72:75], v232 offset:10240
	s_waitcnt lgkmcnt(1)
	v_mfma_f32_16x16x32_bf16 v[64:67], v[64:67], v[4:7], 0
	s_waitcnt lgkmcnt(0)
	v_mfma_f32_16x16x32_bf16 v[64:67], v[72:75], v[0:3], v[64:67]
	ds_read_b128 v[72:75], v233 offset:10240
	ds_read_b128 v[84:87], v234 offset:10240
	s_waitcnt vmcnt(7)
	ds_write_b128 v227, v[100:103] offset:6144
	s_waitcnt vmcnt(6)
	ds_write_b128 v228, v[116:119] offset:6144
	s_waitcnt vmcnt(5)
	ds_write_b128 v229, v[120:123] offset:6144
	s_waitcnt vmcnt(4)
	ds_write_b128 v230, v[128:131] offset:6144
	s_waitcnt lgkmcnt(5)
	v_mfma_f32_16x16x32_bf16 v[64:67], v[72:75], v[12:15], v[64:67]
	ds_read_b128 v[72:75], v231 offset:6144
	s_waitcnt lgkmcnt(5)
	v_mfma_f32_16x16x32_bf16 v[64:67], v[84:87], v[8:11], v[64:67]
	ds_read_b128 v[84:87], v232 offset:6144
	s_waitcnt lgkmcnt(1)
	v_mfma_f32_16x16x32_bf16 v[72:75], v[72:75], v[4:7], 0
	s_waitcnt lgkmcnt(0)
	v_mfma_f32_16x16x32_bf16 v[72:75], v[84:87], v[0:3], v[72:75]
	ds_read_b128 v[84:87], v233 offset:6144
	ds_read_b128 v[88:91], v234 offset:6144
	s_waitcnt vmcnt(3)
	ds_write_b128 v227, v[68:71] offset:10240
	s_waitcnt vmcnt(2)
	ds_write_b128 v228, v[160:163] offset:10240
	s_waitcnt vmcnt(1)
	ds_write_b128 v229, v[80:83] offset:10240
	s_waitcnt vmcnt(0)
	ds_write_b128 v230, v[164:167] offset:10240
	ds_read_b128 v[68:71], v231 offset:10240
	ds_read_b128 v[80:83], v232 offset:10240
	s_waitcnt lgkmcnt(7)
	v_mfma_f32_16x16x32_bf16 v[72:75], v[84:87], v[12:15], v[72:75]
	ds_read_b128 v[84:87], v233 offset:10240
	s_waitcnt lgkmcnt(2)
	v_mfma_f32_16x16x32_bf16 v[68:71], v[68:71], v[4:7], 0
	s_waitcnt lgkmcnt(1)
	v_mfma_f32_16x16x32_bf16 v[68:71], v[80:83], v[0:3], v[68:71]
	ds_read_b128 v[80:83], v234 offset:10240
	s_waitcnt lgkmcnt(1)
	v_mfma_f32_16x16x32_bf16 v[68:71], v[84:87], v[12:15], v[68:71]
	v_mfma_f32_16x16x32_bf16 v[72:75], v[88:91], v[8:11], v[72:75]
	s_waitcnt lgkmcnt(0)
	v_mfma_f32_16x16x32_bf16 v[68:71], v[80:83], v[8:11], v[68:71]
	s_and_saveexec_b64 s[2:3], s[0:1]
	s_cbranch_execz .LBB0_2282
; #define LAS __attribute__((address_space(3)))
; #define ATT_FENCE() asm volatile("" ::: "memory")
; DI void attn_worker(unsigned char* ws, LAS unsigned char* lds, LAS unsigned* qctr, int wave) {
;     ...
;         if (qn2 < SEQ && kr < 4) { const int mq2 = b * SEQ + qn2;
; #pragma unroll
;             for (int ks = 0; ks < 4; ++ks) qf[ks] = *(const bf16x8*)(q + (size_t)mq2 * DA + (4 * g + kr) * 128 + 32 * ks + 8 * kq); }
;         ATT_FENCE();
;         v4i ix[3][2]; v4u vv[3][8];
; #pragma unroll
;         for (int ch = 0; ch < 2; ++ch) {
;             ix[ch][0] = *(const LAS v4i*)(idl + 64 * kg + 8 * ch); ix[ch][1] = *(const LAS v4i*)(idl + 64 * kg + 8 * ch + 4);
; #pragma unroll
;             for (int j = 0; j < 8; ++j) vv[ch][j] = *(const v4u*)(vbase + (size_t)ix[ch][j >> 2][j & 3] * KVD);
;             ATT_FENCE(); }
;         float mx = -3.0e38f;
; #pragma unroll
;         for (int kt = 0; kt < 16; ++kt)
; #pragma unroll
;             for (int e = 0; e < 4; ++e) { const bool ok = (64 * kq + 4 * kt + e) < nvalid; s[kt][e] = ok ? s[kt][e] * 0.08838834764831845f : -3.0e38f; mx = fmaxf(mx, s[kt][e]); }
;         mx = fmaxf(mx, __shfl_xor(mx, 16)); mx = fmaxf(mx, __shfl_xor(mx, 32));
	v_readlane_b32 s0, v253, 43
	v_readlane_b32 s1, v253, 45
	s_add_i32 s0, s1, s0
	s_ashr_i32 s1, s0, 31
	s_lshl_b64 s[0:1], s[0:1], 12
	v_lshl_add_u64 v[8:9], v[140:141], 0, s[0:1]
	global_load_dwordx4 v[4:7], v[8:9], off
	global_load_dwordx4 v[0:3], v[8:9], off offset:64
	global_load_dwordx4 v[12:15], v[8:9], off offset:128
	s_nop 0
	global_load_dwordx4 v[8:11], v[8:9], off offset:192
.LBB0_2282:
	s_or_b64 exec, exec, s[2:3]
	s_min_i32 s60, s33, 0xff
	v_mul_f32_e32 v80, 0x3db504f3, v24
	v_max_f32_e32 v80, 0xff61b1e6, v80
	v_cmp_lt_i32_e64 s[26:27], s60, v183
	v_mul_f32_e32 v81, 0x3db504f3, v25
	v_cmp_gt_i32_e64 s[34:35], s60, v183
	v_cndmask_b32_e64 v80, v80, v239, s[26:27]
	v_or_b32_e32 v82, 2, v183
	v_cndmask_b32_e64 v81, v239, v81, s[34:35]
	v_or_b32_e32 v83, 3, v183
	v_max_f32_e32 v80, v80, v81
	v_mul_f32_e32 v81, 0x3db504f3, v26
	v_cmp_lt_i32_e64 s[28:29], s60, v82
	v_mul_f32_e32 v82, 0x3db504f3, v27
	v_cmp_lt_i32_e64 s[30:31], s60, v83
	v_cndmask_b32_e64 v81, v81, v239, s[28:29]
	v_or_b32_e32 v83, 5, v183
	v_cndmask_b32_e64 v82, v82, v239, s[30:31]
	v_max3_f32 v80, v80, v81, v82
	v_or_b32_e32 v82, 4, v183
	v_mul_f32_e32 v81, 0x3db504f3, v40
	v_cmp_lt_i32_e64 s[22:23], s60, v82
	v_mul_f32_e32 v82, 0x3db504f3, v41
	v_cmp_lt_i32_e64 s[24:25], s60, v83
	v_cndmask_b32_e64 v81, v81, v239, s[22:23]
	v_or_b32_e32 v83, 7, v183
	v_cndmask_b32_e64 v82, v82, v239, s[24:25]
	v_max3_f32 v80, v80, v81, v82
	v_or_b32_e32 v82, 6, v183
	v_mul_f32_e32 v81, 0x3db504f3, v42
	v_cmp_lt_i32_e64 s[18:19], s60, v82
	v_mul_f32_e32 v82, 0x3db504f3, v43
	v_cmp_lt_i32_e64 s[20:21], s60, v83
	v_cndmask_b32_e64 v81, v81, v239, s[18:19]
	v_or_b32_e32 v83, 9, v183
	v_cndmask_b32_e64 v82, v82, v239, s[20:21]
	v_max3_f32 v80, v80, v81, v82
	v_or_b32_e32 v82, 8, v183
	v_mul_f32_e32 v81, 0x3db504f3, v44
	v_cmp_lt_i32_e64 s[14:15], s60, v82
	v_mul_f32_e32 v82, 0x3db504f3, v45
	v_cmp_lt_i32_e64 s[16:17], s60, v83
	v_cndmask_b32_e64 v81, v81, v239, s[14:15]
	v_or_b32_e32 v83, 11, v183
	v_cndmask_b32_e64 v82, v82, v239, s[16:17]
	v_max3_f32 v80, v80, v81, v82
	v_or_b32_e32 v82, 10, v183
	v_mul_f32_e32 v81, 0x3db504f3, v46
	v_cmp_lt_i32_e64 s[10:11], s60, v82
	v_mul_f32_e32 v82, 0x3db504f3, v47
	v_cmp_lt_i32_e64 s[12:13], s60, v83
	v_cndmask_b32_e64 v81, v81, v239, s[10:11]
	v_or_b32_e32 v83, 13, v183
	v_cndmask_b32_e64 v82, v82, v239, s[12:13]
	v_max3_f32 v80, v80, v81, v82
	v_or_b32_e32 v82, 12, v183
	v_mul_f32_e32 v81, 0x3db504f3, v76
	v_cmp_lt_i32_e64 s[6:7], s60, v82
	v_mul_f32_e32 v82, 0x3db504f3, v77
	v_cmp_lt_i32_e64 s[8:9], s60, v83
	v_cndmask_b32_e64 v81, v81, v239, s[6:7]
	v_or_b32_e32 v83, 15, v183
	v_cndmask_b32_e64 v82, v82, v239, s[8:9]
	v_max3_f32 v80, v80, v81, v82
	v_or_b32_e32 v82, 14, v183
	v_mul_f32_e32 v81, 0x3db504f3, v78
	v_cmp_lt_i32_e64 s[2:3], s60, v82
	v_mul_f32_e32 v82, 0x3db504f3, v79
	v_cmp_lt_i32_e64 s[4:5], s60, v83
	v_cndmask_b32_e64 v81, v81, v239, s[2:3]
	v_or_b32_e32 v83, 17, v183
	v_cndmask_b32_e64 v82, v82, v239, s[4:5]
	v_max3_f32 v80, v80, v81, v82
	v_or_b32_e32 v82, 16, v183
	v_mul_f32_e32 v81, 0x3db504f3, v28
	v_cmp_lt_i32_e32 vcc, s60, v82
	v_mul_f32_e32 v82, 0x3db504f3, v29
	v_cmp_lt_i32_e64 s[0:1], s60, v83
	v_cndmask_b32_e32 v81, v81, v239, vcc
	v_or_b32_e32 v83, 19, v183
	v_cndmask_b32_e64 v82, v82, v239, s[0:1]
	v_max3_f32 v80, v80, v81, v82
	v_or_b32_e32 v82, 18, v183
	v_mul_f32_e32 v81, 0x3db504f3, v30
	v_cmp_lt_i32_e64 s[36:37], s60, v82
	v_mul_f32_e32 v82, 0x3db504f3, v31
	v_cmp_lt_i32_e64 s[38:39], s60, v83
	v_cndmask_b32_e64 v81, v81, v239, s[36:37]
	v_cmp_lt_i32_e64 s[56:57], s60, v132
	v_cndmask_b32_e64 v82, v82, v239, s[38:39]
	v_max3_f32 v80, v80, v81, v82
	v_or_b32_e32 v82, 20, v183
	v_mul_f32_e32 v81, 0x3db504f3, v16
	v_cmp_lt_i32_e64 s[96:97], s60, v82
	v_mul_f32_e32 v82, 0x3db504f3, v17
	v_cndmask_b32_e64 v82, v82, v239, s[56:57]
	v_cndmask_b32_e64 v81, v81, v239, s[96:97]
	v_max3_f32 v80, v80, v81, v82
	v_mul_f32_e32 v81, 0x3db504f3, v18
	v_cmp_lt_i32_e64 s[52:53], s60, v185
	v_mul_f32_e32 v82, 0x3db504f3, v19
	v_cmp_lt_i32_e64 s[54:55], s60, v186
	v_cndmask_b32_e64 v81, v81, v239, s[52:53]
	v_cmp_lt_i32_e64 s[48:49], s60, v187
	v_cndmask_b32_e64 v82, v82, v239, s[54:55]
	v_max3_f32 v80, v80, v81, v82
	v_mul_f32_e32 v81, 0x3db504f3, v20
	v_mul_f32_e32 v82, 0x3db504f3, v21
	v_cmp_lt_i32_e64 s[50:51], s60, v188
	v_cndmask_b32_e64 v81, v81, v239, s[48:49]
	v_cmp_lt_i32_e64 s[44:45], s60, v189
	v_cndmask_b32_e64 v82, v82, v239, s[50:51]
	v_max3_f32 v80, v80, v81, v82
	v_mul_f32_e32 v81, 0x3db504f3, v22
	v_mul_f32_e32 v82, 0x3db504f3, v23
	v_cmp_lt_i32_e64 s[46:47], s60, v190
	v_cndmask_b32_e64 v81, v81, v239, s[44:45]
	v_cmp_lt_i32_e64 s[40:41], s60, v191
	v_cndmask_b32_e64 v82, v82, v239, s[46:47]
	v_max3_f32 v80, v80, v81, v82
	v_mul_f32_e32 v81, 0x3db504f3, v36
	v_writelane_b32 v253, s40, 9
	v_mul_f32_e32 v82, 0x3db504f3, v37
	v_cmp_lt_i32_e64 s[42:43], s60, v192
	v_writelane_b32 v253, s41, 10
	v_cndmask_b32_e64 v81, v81, v239, s[40:41]
	v_cndmask_b32_e64 v82, v82, v239, s[42:43]
	v_cmp_lt_i32_e64 s[40:41], s60, v193
	v_max3_f32 v80, v80, v81, v82
	v_mul_f32_e32 v81, 0x3db504f3, v38
	v_writelane_b32 v253, s40, 13
	v_mul_f32_e32 v82, 0x3db504f3, v39
	v_cmp_lt_i32_e64 s[94:95], s60, v208
	v_writelane_b32 v253, s41, 14
	v_cndmask_b32_e64 v81, v81, v239, s[40:41]
	v_cmp_lt_i32_e64 s[40:41], s60, v194
	v_cmp_lt_i32_e64 s[90:91], s60, v209
	v_cmp_lt_i32_e64 s[92:93], s60, v210
	v_writelane_b32 v253, s40, 11
	v_cmp_lt_i32_e64 s[86:87], s60, v211
	v_cmp_lt_i32_e64 s[88:89], s60, v212
	v_writelane_b32 v253, s41, 12
	v_cndmask_b32_e64 v82, v82, v239, s[40:41]
	v_cmp_lt_i32_e64 s[40:41], s60, v195
	v_max3_f32 v80, v80, v81, v82
; DI void attn_worker(unsigned char* ws, LAS unsigned char* lds, LAS unsigned* qctr, int wave) {
;     ...
;         float mx = -3.0e38f;
; #pragma unroll
;         for (int kt = 0; kt < 16; ++kt)
; #pragma unroll
;             for (int e = 0; e < 4; ++e) { const bool ok = (64 * kq + 4 * kt + e) < nvalid; s[kt][e] = ok ? s[kt][e] * 0.08838834764831845f : -3.0e38f; mx = fmaxf(mx, s[kt][e]); }
;         mx = fmaxf(mx, __shfl_xor(mx, 16)); mx = fmaxf(mx, __shfl_xor(mx, 32));
	v_mul_f32_e32 v81, 0x3db504f3, v32
	v_writelane_b32 v253, s40, 17
	v_mul_f32_e32 v82, 0x3db504f3, v33
	v_cmp_lt_i32_e64 s[82:83], s60, v213
	v_writelane_b32 v253, s41, 18
	v_cndmask_b32_e64 v81, v81, v239, s[40:41]
	v_cmp_lt_i32_e64 s[40:41], s60, v196
	v_cmp_lt_i32_e64 s[84:85], s60, v214
	v_cmp_lt_i32_e64 s[80:81], s60, v216
	v_writelane_b32 v253, s40, 15
	v_cmp_lt_i32_e64 s[74:75], s60, v217
	v_cmp_lt_i32_e64 s[76:77], s60, v218
	v_writelane_b32 v253, s41, 16
	v_cndmask_b32_e64 v82, v82, v239, s[40:41]
	v_cmp_lt_i32_e64 s[40:41], s60, v197
	v_max3_f32 v80, v80, v81, v82
	v_mul_f32_e32 v81, 0x3db504f3, v34
	v_writelane_b32 v253, s40, 21
	v_mul_f32_e32 v82, 0x3db504f3, v35
	v_cmp_lt_i32_e64 s[70:71], s60, v219
	v_writelane_b32 v253, s41, 22
	v_cndmask_b32_e64 v81, v81, v239, s[40:41]
	v_cmp_lt_i32_e64 s[40:41], s60, v198
	v_cmp_lt_i32_e64 s[72:73], s60, v220
	v_and_b32_e32 v84, 64, v235
	v_writelane_b32 v253, s40, 19
	v_cmp_lt_i32_e64 s[66:67], s60, v221
	v_cmp_lt_i32_e64 s[68:69], s60, v222
	v_writelane_b32 v253, s41, 20
	v_cndmask_b32_e64 v82, v82, v239, s[40:41]
	v_cmp_lt_i32_e64 s[40:41], s60, v199
	v_max3_f32 v80, v80, v81, v82
	v_mul_f32_e32 v81, 0x3db504f3, v60
	v_writelane_b32 v253, s40, 25
	v_mul_f32_e32 v82, 0x3db504f3, v61
	v_xor_b32_e32 v83, 16, v235
	v_writelane_b32 v253, s41, 26
	v_cndmask_b32_e64 v81, v81, v239, s[40:41]
	v_cmp_lt_i32_e64 s[40:41], s60, v200
	v_add_u32_e32 v84, 64, v84
	v_cmp_lt_i32_e64 s[58:59], v83, v84
	v_writelane_b32 v253, s40, 23
	v_xor_b32_e32 v85, 32, v235
	v_cmp_lt_i32_e64 s[62:63], s60, v223
	v_writelane_b32 v253, s41, 24
	v_cndmask_b32_e64 v82, v82, v239, s[40:41]
	v_cmp_lt_i32_e64 s[40:41], s60, v201
	v_max3_f32 v80, v80, v81, v82
	v_mul_f32_e32 v81, 0x3db504f3, v62
	v_writelane_b32 v253, s40, 29
	v_mul_f32_e32 v82, 0x3db504f3, v63
	v_cmp_lt_i32_e64 s[64:65], s60, v224
	v_writelane_b32 v253, s41, 30
	v_cndmask_b32_e64 v81, v81, v239, s[40:41]
	v_cmp_lt_i32_e64 s[40:41], s60, v202
	v_cndmask_b32_e64 v83, v235, v83, s[58:59]
	v_cmp_lt_i32_e64 s[58:59], v85, v84
	v_writelane_b32 v253, s40, 27
	v_lshlrev_b32_e32 v241, 2, v83
	v_cndmask_b32_e64 v84, v235, v85, s[58:59]
	v_writelane_b32 v253, s41, 28
	v_cndmask_b32_e64 v82, v82, v239, s[40:41]
	v_cmp_lt_i32_e64 s[40:41], s60, v203
	v_max3_f32 v80, v80, v81, v82
	v_mul_f32_e32 v81, 0x3db504f3, v52
	v_writelane_b32 v253, s40, 33
	v_mul_f32_e32 v82, 0x3db504f3, v53
	v_cmp_lt_i32_e64 s[58:59], s60, v225
	v_writelane_b32 v253, s41, 34
	v_cndmask_b32_e64 v81, v81, v239, s[40:41]
	v_cmp_lt_i32_e64 s[40:41], s60, v204
	v_lshlrev_b32_e32 v240, 2, v84
	s_nop 0
	v_writelane_b32 v253, s40, 31
	s_nop 1
	v_writelane_b32 v253, s41, 32
	v_cndmask_b32_e64 v82, v82, v239, s[40:41]
	v_cmp_lt_i32_e64 s[40:41], s60, v205
	v_max3_f32 v80, v80, v81, v82
	v_mul_f32_e32 v81, 0x3db504f3, v54
	v_writelane_b32 v253, s40, 37
	v_mul_f32_e32 v82, 0x3db504f3, v55
	s_nop 0
	v_writelane_b32 v253, s41, 38
	v_cndmask_b32_e64 v81, v81, v239, s[40:41]
	v_cmp_lt_i32_e64 s[40:41], s60, v206
	s_nop 1
	v_writelane_b32 v253, s40, 35
	s_nop 1
	v_cndmask_b32_e64 v82, v82, v239, s[40:41]
	v_writelane_b32 v253, s41, 36
	v_max3_f32 v80, v80, v81, v82
	v_mul_f32_e32 v81, 0x3db504f3, v48
	v_cmp_lt_i32_e64 s[40:41], s60, v207
	v_mul_f32_e32 v82, 0x3db504f3, v49
	v_cndmask_b32_e64 v82, v82, v239, s[94:95]
	v_writelane_b32 v253, s40, 39
	s_nop 1
	v_cndmask_b32_e64 v81, v81, v239, s[40:41]
	v_max3_f32 v80, v80, v81, v82
	v_mul_f32_e32 v81, 0x3db504f3, v50
	v_mul_f32_e32 v82, 0x3db504f3, v51
	v_cndmask_b32_e64 v81, v81, v239, s[90:91]
	v_cndmask_b32_e64 v82, v82, v239, s[92:93]
	v_max3_f32 v80, v80, v81, v82
	v_mul_f32_e32 v81, 0x3db504f3, v56
	v_mul_f32_e32 v82, 0x3db504f3, v57
	v_cndmask_b32_e64 v81, v81, v239, s[86:87]
	v_cndmask_b32_e64 v82, v82, v239, s[88:89]
	v_max3_f32 v80, v80, v81, v82
	v_mul_f32_e32 v81, 0x3db504f3, v58
	v_mul_f32_e32 v82, 0x3db504f3, v59
	v_cndmask_b32_e64 v81, v81, v239, s[82:83]
	v_cndmask_b32_e64 v82, v82, v239, s[84:85]
	v_writelane_b32 v253, s41, 40
	v_max3_f32 v80, v80, v81, v82
	v_mul_f32_e32 v81, 0x3db504f3, v64
	v_cmp_lt_i32_e64 s[40:41], s60, v215
	v_mul_f32_e32 v82, 0x3db504f3, v65
	v_cndmask_b32_e64 v82, v82, v239, s[80:81]
	v_cndmask_b32_e64 v81, v81, v239, s[40:41]
	v_max3_f32 v80, v80, v81, v82
	v_mul_f32_e32 v81, 0x3db504f3, v66
	v_mul_f32_e32 v82, 0x3db504f3, v67
	v_cndmask_b32_e64 v81, v81, v239, s[74:75]
	v_cndmask_b32_e64 v82, v82, v239, s[76:77]
	v_max3_f32 v80, v80, v81, v82
	v_mul_f32_e32 v81, 0x3db504f3, v72
	v_mul_f32_e32 v82, 0x3db504f3, v73
	v_cndmask_b32_e64 v81, v81, v239, s[70:71]
	v_cndmask_b32_e64 v82, v82, v239, s[72:73]
	v_max3_f32 v80, v80, v81, v82
	v_mul_f32_e32 v81, 0x3db504f3, v74
	v_mul_f32_e32 v82, 0x3db504f3, v75
	v_cndmask_b32_e64 v81, v81, v239, s[66:67]
	v_cndmask_b32_e64 v82, v82, v239, s[68:69]
	v_max3_f32 v80, v80, v81, v82
	v_mul_f32_e32 v81, 0x3db504f3, v68
	v_mul_f32_e32 v82, 0x3db504f3, v69
	v_cndmask_b32_e64 v81, v81, v239, s[62:63]
	v_cndmask_b32_e64 v82, v82, v239, s[64:65]
	v_max3_f32 v80, v80, v81, v82
	v_mul_f32_e32 v81, 0x3db504f3, v70
	v_mul_f32_e32 v82, 0x3db504f3, v71
	v_cmp_lt_i32_e64 s[60:61], s60, v226
	v_cndmask_b32_e64 v81, v81, v239, s[58:59]
	s_nop 0
	v_cndmask_b32_e64 v82, v82, v239, s[60:61]
	v_max3_f32 v80, v80, v81, v82
	ds_bpermute_b32 v81, v241, v80
	s_waitcnt lgkmcnt(0)
	v_max_f32_e32 v81, v81, v81
	v_max_f32_e32 v80, v80, v81
	ds_bpermute_b32 v81, v240, v80
	s_waitcnt lgkmcnt(0)
; #define LAS __attribute__((address_space(3)))
; #define ATT_FENCE() asm volatile("" ::: "memory")
; DI void attn_worker(unsigned char* ws, LAS unsigned char* lds, LAS unsigned* qctr, int wave) {
;     ...
;         v4i ix[3][2]; v4u vv[3][8];
; #pragma unroll
;         for (int ch = 0; ch < 2; ++ch) {
;             ix[ch][0] = *(const LAS v4i*)(idl + 64 * kg + 8 * ch); ix[ch][1] = *(const LAS v4i*)(idl + 64 * kg + 8 * ch + 4);
; #pragma unroll
;             for (int j = 0; j < 8; ++j) vv[ch][j] = *(const v4u*)(vbase + (size_t)ix[ch][j >> 2][j & 3] * KVD);
;             ATT_FENCE(); }
;     ...
;         float sum = 0.f;
; #pragma unroll
;         for (int kt = 0; kt < 16; ++kt)
; #pragma unroll
;             for (int e = 0; e < 4; ++e) { const bool ok = (64 * kq + 4 * kt + e) < nvalid; const float p = ok ? __expf(s[kt][e] - mx) : 0.f; s[kt][e] = p; sum += p; }
	v_max_f32_e32 v81, v81, v81
	v_max_f32_e32 v242, v80, v81
	v_fma_f32 v24, v24, s78, -v242
	v_mul_f32_e32 v24, 0x3fb8aa3b, v24
	v_exp_f32_e32 v24, v24
	v_fma_f32 v30, v30, s78, -v242
	v_mul_f32_e32 v30, 0x3fb8aa3b, v30
	v_fma_f32 v31, v31, s78, -v242
	v_cndmask_b32_e64 v124, v24, 0, s[26:27]
	v_fma_f32 v24, v25, s78, -v242
	v_mul_f32_e32 v24, 0x3fb8aa3b, v24
	v_exp_f32_e32 v24, v24
	v_exp_f32_e32 v30, v30
	v_mul_f32_e32 v31, 0x3fb8aa3b, v31
	v_fma_f32 v16, v16, s78, -v242
	v_cndmask_b32_e64 v125, 0, v24, s[34:35]
	v_fma_f32 v24, v26, s78, -v242
	v_mul_f32_e32 v24, 0x3fb8aa3b, v24
	v_exp_f32_e32 v24, v24
	v_exp_f32_e32 v31, v31
	v_mul_f32_e32 v16, 0x3fb8aa3b, v16
	v_fma_f32 v17, v17, s78, -v242
	v_cndmask_b32_e64 v128, v24, 0, s[28:29]
	v_fma_f32 v24, v27, s78, -v242
	v_mul_f32_e32 v24, 0x3fb8aa3b, v24
	v_exp_f32_e32 v24, v24
	v_exp_f32_e32 v16, v16
	v_mul_f32_e32 v17, 0x3fb8aa3b, v17
	v_fma_f32 v18, v18, s78, -v242
	v_cndmask_b32_e64 v129, v24, 0, s[30:31]
	v_fma_f32 v24, v40, s78, -v242
	v_mul_f32_e32 v24, 0x3fb8aa3b, v24
	v_exp_f32_e32 v24, v24
	v_exp_f32_e32 v17, v17
	v_mul_f32_e32 v18, 0x3fb8aa3b, v18
	v_fma_f32 v19, v19, s78, -v242
	v_cndmask_b32_e64 v130, v24, 0, s[22:23]
	v_fma_f32 v24, v41, s78, -v242
	v_mul_f32_e32 v24, 0x3fb8aa3b, v24
	v_exp_f32_e32 v24, v24
	v_cndmask_b32_e64 v30, v30, 0, s[36:37]
	v_exp_f32_e32 v18, v18
	v_mul_f32_e32 v19, 0x3fb8aa3b, v19
	v_cndmask_b32_e64 v131, v24, 0, s[24:25]
	v_fma_f32 v24, v42, s78, -v242
	v_mul_f32_e32 v24, 0x3fb8aa3b, v24
	v_exp_f32_e32 v24, v24
	v_cndmask_b32_e64 v31, v31, 0, s[38:39]
	v_exp_f32_e32 v19, v19
	v_cndmask_b32_e64 v16, v16, 0, s[96:97]
	v_cndmask_b32_e64 v148, v24, 0, s[18:19]
	v_fma_f32 v24, v43, s78, -v242
	v_mul_f32_e32 v24, 0x3fb8aa3b, v24
	v_exp_f32_e32 v24, v24
	v_cndmask_b32_e64 v17, v17, 0, s[56:57]
	v_fma_f32 v32, v32, s78, -v242
	v_mul_f32_e32 v32, 0x3fb8aa3b, v32
	v_cndmask_b32_e64 v149, v24, 0, s[20:21]
	v_fma_f32 v24, v44, s78, -v242
	v_mul_f32_e32 v24, 0x3fb8aa3b, v24
	v_exp_f32_e32 v24, v24
	v_exp_f32_e32 v32, v32
	v_fma_f32 v33, v33, s78, -v242
	v_mul_f32_e32 v33, 0x3fb8aa3b, v33
	v_cndmask_b32_e64 v126, v24, 0, s[14:15]
	v_fma_f32 v24, v45, s78, -v242
	v_mul_f32_e32 v24, 0x3fb8aa3b, v24
	v_exp_f32_e32 v24, v24
	v_exp_f32_e32 v33, v33
	v_fma_f32 v34, v34, s78, -v242
	v_mul_f32_e32 v34, 0x3fb8aa3b, v34
	v_cndmask_b32_e64 v127, v24, 0, s[16:17]
	v_fma_f32 v24, v46, s78, -v242
	v_mul_f32_e32 v24, 0x3fb8aa3b, v24
	v_exp_f32_e32 v24, v24
	v_exp_f32_e32 v34, v34
	v_fma_f32 v35, v35, s78, -v242
	v_mul_f32_e32 v35, 0x3fb8aa3b, v35
	v_cndmask_b32_e64 v144, v24, 0, s[10:11]
	v_fma_f32 v24, v47, s78, -v242
	v_mul_f32_e32 v24, 0x3fb8aa3b, v24
	v_exp_f32_e32 v24, v24
	v_exp_f32_e32 v35, v35
	v_cndmask_b32_e64 v145, v24, 0, s[12:13]
	v_fma_f32 v24, v76, s78, -v242
	v_mul_f32_e32 v24, 0x3fb8aa3b, v24
	v_exp_f32_e32 v24, v24
	s_nop 0
	v_cndmask_b32_e64 v146, v24, 0, s[6:7]
	v_fma_f32 v24, v77, s78, -v242
	v_mul_f32_e32 v24, 0x3fb8aa3b, v24
	v_exp_f32_e32 v24, v24
	s_nop 0
	v_cndmask_b32_e64 v147, v24, 0, s[8:9]
	v_fma_f32 v24, v78, s78, -v242
	v_mul_f32_e32 v24, 0x3fb8aa3b, v24
	v_exp_f32_e32 v24, v24
	s_nop 0
	v_cndmask_b32_e64 v150, v24, 0, s[2:3]
	v_fma_f32 v24, v79, s78, -v242
	v_mul_f32_e32 v24, 0x3fb8aa3b, v24
	v_exp_f32_e32 v24, v24
	s_nop 0
	v_cndmask_b32_e64 v151, v24, 0, s[4:5]
	v_fma_f32 v24, v28, s78, -v242
	v_mul_f32_e32 v24, 0x3fb8aa3b, v24
	v_exp_f32_e32 v24, v24
	s_nop 0
	v_cndmask_b32_e64 v28, v24, 0, vcc
	v_fma_f32 v24, v29, s78, -v242
	v_mul_f32_e32 v24, 0x3fb8aa3b, v24
	v_exp_f32_e32 v24, v24
	s_nop 0
	v_cndmask_b32_e64 v29, v24, 0, s[0:1]
	ds_read_b128 v[24:27], v182
	ds_read_b128 v[40:43], v182 offset:16
	v_readlane_b32 s0, v253, 9
	v_readlane_b32 s1, v253, 10
	s_waitcnt lgkmcnt(1)
	v_lshl_add_u32 v44, v24, 10, v252
	v_lshl_add_u32 v46, v25, 10, v252
	global_load_dwordx4 v[88:91], v44, s[100:101]
	global_load_dwordx4 v[92:95], v46, s[100:101]
	v_lshl_add_u32 v24, v26, 10, v252
	v_lshl_add_u32 v44, v27, 10, v252
	global_load_dwordx4 v[96:99], v24, s[100:101]
	global_load_dwordx4 v[100:103], v44, s[100:101]
	s_waitcnt lgkmcnt(0)
	v_lshl_add_u32 v24, v40, 10, v252
	v_lshl_add_u32 v26, v41, 10, v252
	global_load_dwordx4 v[104:107], v24, s[100:101]
	global_load_dwordx4 v[108:111], v26, s[100:101]
	v_lshl_add_u32 v24, v42, 10, v252
	v_lshl_add_u32 v26, v43, 10, v252
	global_load_dwordx4 v[112:115], v24, s[100:101]
	global_load_dwordx4 v[116:119], v26, s[100:101]
	ds_read_b128 v[42:45], v182 offset:32
	ds_read_b128 v[120:123], v182 offset:48
	s_waitcnt lgkmcnt(1)
	s_waitcnt lgkmcnt(0)
; DI void attn_worker(unsigned char* ws, LAS unsigned char* lds, LAS unsigned* qctr, int wave) {
;     ...
; #pragma unroll
;         for (int kt = 0; kt < 16; ++kt)
; #pragma unroll
;             for (int e = 0; e < 4; ++e) { const bool ok = (64 * kq + 4 * kt + e) < nvalid; const float p = ok ? __expf(s[kt][e] - mx) : 0.f; s[kt][e] = p; sum += p; }
	v_lshl_add_u32 v80, v120, 10, v252
	v_add_f32_e32 v120, 0, v124
	v_add_f32_e32 v120, v125, v120
	v_add_f32_e32 v120, v128, v120
	v_add_f32_e32 v120, v129, v120
	v_add_f32_e32 v120, v130, v120
	v_add_f32_e32 v120, v131, v120
	v_add_f32_e32 v120, v148, v120
	v_add_f32_e32 v120, v149, v120
	v_add_f32_e32 v120, v126, v120
	v_add_f32_e32 v120, v127, v120
	v_add_f32_e32 v120, v144, v120
	v_add_f32_e32 v120, v145, v120
	v_add_f32_e32 v120, v146, v120
	v_add_f32_e32 v120, v147, v120
	v_add_f32_e32 v120, v150, v120
	v_add_f32_e32 v120, v151, v120
	v_add_f32_e32 v120, v28, v120
	v_add_f32_e32 v120, v29, v120
	v_add_f32_e32 v120, v30, v120
	v_add_f32_e32 v120, v31, v120
	v_add_f32_e32 v120, v16, v120
	v_lshl_add_u32 v82, v121, 10, v252
	v_add_f32_e32 v121, v17, v120
	v_cndmask_b32_e64 v120, v18, 0, s[52:53]
	v_add_f32_e32 v18, v120, v121
	v_cndmask_b32_e64 v121, v19, 0, s[54:55]
	v_fma_f32 v19, v20, s78, -v242
	v_fma_f32 v20, v21, s78, -v242
	v_mul_f32_e32 v19, 0x3fb8aa3b, v19
	v_mul_f32_e32 v20, 0x3fb8aa3b, v20
	v_exp_f32_e32 v19, v19
	v_exp_f32_e32 v20, v20
	v_add_f32_e32 v21, v121, v18
	v_lshl_add_u32 v24, v42, 10, v252
	v_cndmask_b32_e64 v18, v19, 0, s[48:49]
	v_cndmask_b32_e64 v19, v20, 0, s[50:51]
	v_fma_f32 v20, v22, s78, -v242
	v_mul_f32_e32 v20, 0x3fb8aa3b, v20
	v_fma_f32 v22, v23, s78, -v242
	v_exp_f32_e32 v20, v20
	v_mul_f32_e32 v22, 0x3fb8aa3b, v22
	v_exp_f32_e32 v22, v22
	v_add_f32_e32 v21, v18, v21
	v_add_f32_e32 v21, v19, v21
	v_cndmask_b32_e64 v20, v20, 0, s[44:45]
	v_add_f32_e32 v23, v20, v21
	v_cndmask_b32_e64 v21, v22, 0, s[46:47]
	v_fma_f32 v22, v36, s78, -v242
	v_mul_f32_e32 v22, 0x3fb8aa3b, v22
	v_fma_f32 v36, v37, s78, -v242
	v_exp_f32_e32 v22, v22
	v_mul_f32_e32 v36, 0x3fb8aa3b, v36
	v_exp_f32_e32 v36, v36
	v_add_f32_e32 v23, v21, v23
	v_cndmask_b32_e64 v22, v22, 0, s[0:1]
	v_add_f32_e32 v37, v22, v23
	v_cndmask_b32_e64 v23, v36, 0, s[42:43]
	v_fma_f32 v36, v38, s78, -v242
	v_mul_f32_e32 v36, 0x3fb8aa3b, v36
	v_exp_f32_e32 v36, v36
	v_fma_f32 v38, v39, s78, -v242
	v_mul_f32_e32 v38, 0x3fb8aa3b, v38
	v_exp_f32_e32 v38, v38
	v_readlane_b32 s0, v253, 13
	v_readlane_b32 s1, v253, 14
	v_add_f32_e32 v37, v23, v37
	s_nop 0
	v_cndmask_b32_e64 v36, v36, 0, s[0:1]
	v_readlane_b32 s0, v253, 11
	v_readlane_b32 s1, v253, 12
	v_add_f32_e32 v39, v36, v37
	s_nop 0
	v_cndmask_b32_e64 v37, v38, 0, s[0:1]
	v_readlane_b32 s0, v253, 17
	v_readlane_b32 s1, v253, 18
	v_add_f32_e32 v38, v37, v39
	v_fma_f32 v39, v60, s78, -v242
	v_cndmask_b32_e64 v32, v32, 0, s[0:1]
	v_readlane_b32 s0, v253, 15
	v_readlane_b32 s1, v253, 16
	v_mul_f32_e32 v39, 0x3fb8aa3b, v39
	v_exp_f32_e32 v39, v39
	v_cndmask_b32_e64 v33, v33, 0, s[0:1]
	v_readlane_b32 s0, v253, 21
	v_readlane_b32 s1, v253, 22
	v_fma_f32 v60, v61, s78, -v242
	v_mul_f32_e32 v60, 0x3fb8aa3b, v60
	v_cndmask_b32_e64 v34, v34, 0, s[0:1]
	v_readlane_b32 s0, v253, 19
	v_readlane_b32 s1, v253, 20
	v_exp_f32_e32 v60, v60
	v_add_f32_e32 v38, v32, v38
	v_cndmask_b32_e64 v35, v35, 0, s[0:1]
	v_readlane_b32 s0, v253, 25
	v_readlane_b32 s1, v253, 26
	v_add_f32_e32 v38, v33, v38
	v_add_f32_e32 v38, v34, v38
	v_cndmask_b32_e64 v152, v39, 0, s[0:1]
	v_fma_f32 v39, v62, s78, -v242
	v_mul_f32_e32 v39, 0x3fb8aa3b, v39
	v_readlane_b32 s0, v253, 23
	v_exp_f32_e32 v39, v39
	v_readlane_b32 s1, v253, 24
	v_add_f32_e32 v38, v35, v38
	v_add_f32_e32 v38, v152, v38
	v_cndmask_b32_e64 v153, v60, 0, s[0:1]
	v_fma_f32 v60, v63, s78, -v242
	v_readlane_b32 s0, v253, 29
	v_mul_f32_e32 v60, 0x3fb8aa3b, v60
	v_readlane_b32 s1, v253, 30
	v_exp_f32_e32 v60, v60
	v_add_f32_e32 v38, v153, v38
	v_cndmask_b32_e64 v156, v39, 0, s[0:1]
	v_fma_f32 v39, v52, s78, -v242
	v_mul_f32_e32 v39, 0x3fb8aa3b, v39
	v_readlane_b32 s0, v253, 27
	v_exp_f32_e32 v39, v39
	v_readlane_b32 s1, v253, 28
	v_fma_f32 v52, v53, s78, -v242
	v_mul_f32_e32 v52, 0x3fb8aa3b, v52
	v_cndmask_b32_e64 v157, v60, 0, s[0:1]
	v_readlane_b32 s0, v253, 33
	v_readlane_b32 s1, v253, 34
	v_exp_f32_e32 v52, v52
	v_add_f32_e32 v38, v156, v38
	v_cndmask_b32_e64 v154, v39, 0, s[0:1]
	v_fma_f32 v39, v54, s78, -v242
	v_mul_f32_e32 v39, 0x3fb8aa3b, v39
	v_readlane_b32 s0, v253, 31
	v_exp_f32_e32 v39, v39
	v_readlane_b32 s1, v253, 32
	v_add_f32_e32 v38, v157, v38
	v_add_f32_e32 v38, v154, v38
	v_cndmask_b32_e64 v155, v52, 0, s[0:1]
	v_fma_f32 v52, v55, s78, -v242
	v_readlane_b32 s0, v253, 37
	v_mul_f32_e32 v52, 0x3fb8aa3b, v52
	v_readlane_b32 s1, v253, 38
	v_exp_f32_e32 v52, v52
	v_add_f32_e32 v38, v155, v38
	v_cndmask_b32_e64 v158, v39, 0, s[0:1]
	v_fma_f32 v39, v48, s78, -v242
	v_mul_f32_e32 v39, 0x3fb8aa3b, v39
	v_fma_f32 v48, v49, s78, -v242
	v_readlane_b32 s0, v253, 35
	v_exp_f32_e32 v39, v39
	v_mul_f32_e32 v48, 0x3fb8aa3b, v48
	v_readlane_b32 s1, v253, 36
	v_exp_f32_e32 v48, v48
	v_add_f32_e32 v38, v158, v38
	v_cndmask_b32_e64 v159, v52, 0, s[0:1]
	v_readlane_b32 s0, v253, 39
	v_readlane_b32 s1, v253, 40
	v_cndmask_b32_e64 v161, v48, 0, s[94:95]
	v_fma_f32 v48, v51, s78, -v242
	v_cndmask_b32_e64 v160, v39, 0, s[0:1]
	v_fma_f32 v39, v50, s78, -v242
	v_mul_f32_e32 v39, 0x3fb8aa3b, v39
	v_exp_f32_e32 v39, v39
	v_mul_f32_e32 v48, 0x3fb8aa3b, v48
	v_exp_f32_e32 v48, v48
	v_add_f32_e32 v38, v159, v38
	v_cndmask_b32_e64 v164, v39, 0, s[90:91]
	v_fma_f32 v39, v56, s78, -v242
	v_cndmask_b32_e64 v165, v48, 0, s[92:93]
	v_mul_f32_e32 v39, 0x3fb8aa3b, v39
	v_fma_f32 v48, v57, s78, -v242
	v_exp_f32_e32 v39, v39
	v_mul_f32_e32 v48, 0x3fb8aa3b, v48
	v_exp_f32_e32 v48, v48
	v_add_f32_e32 v38, v160, v38
	v_cndmask_b32_e64 v162, v39, 0, s[86:87]
	v_fma_f32 v39, v58, s78, -v242
	v_cndmask_b32_e64 v163, v48, 0, s[88:89]
	v_mul_f32_e32 v39, 0x3fb8aa3b, v39
	v_fma_f32 v48, v59, s78, -v242
	v_exp_f32_e32 v39, v39
; #define LAS __attribute__((address_space(3)))
; DI v4u pack8(const f4& a, const f4& b) { v4u w; w.x = cvt_pk_bf16(a[0], a[1]); w.y = cvt_pk_bf16(a[2], a[3]); w.z = cvt_pk_bf16(b[0], b[1]); w.w = cvt_pk_bf16(b[2], b[3]); return w; }
; #define ATT_FENCE() asm volatile("" ::: "memory")
; DI void attn_worker(unsigned char* ws, LAS unsigned char* lds, LAS unsigned* qctr, int wave) {
;     ...
; #pragma unroll
;         for (int kt = 0; kt < 16; ++kt)
; #pragma unroll
;             for (int e = 0; e < 4; ++e) { const bool ok = (64 * kq + 4 * kt + e) < nvalid; const float p = ok ? __expf(s[kt][e] - mx) : 0.f; s[kt][e] = p; sum += p; }
;         sum += __shfl_xor(sum, 16); sum += __shfl_xor(sum, 32);
;         const float inv = 1.0f / sum;
;         bf16x8 pa[8];
; #pragma unroll
;         for (int sg = 0; sg < 8; ++sg) pa[sg] = __builtin_bit_cast(bf16x8, epi::pack8(s[2 * sg] * inv, s[2 * sg + 1] * inv));
;     ...
;         for (int ch = 0; ch < 8; ++ch) {
;             if (ch + 2 < 8) { const int c2 = (ch + 2) % 3;
;                 ix[c2][0] = *(const LAS v4i*)(idl + 64 * kg + 8 * (ch + 2)); ix[c2][1] = *(const LAS v4i*)(idl + 64 * kg + 8 * (ch + 2) + 4);
; #pragma unroll
;                 for (int j = 0; j < 8; ++j) vv[c2][j] = *(const v4u*)(vbase + (size_t)ix[c2][j >> 2][j & 3] * KVD);
;                 ATT_FENCE(); }
	v_mul_f32_e32 v48, 0x3fb8aa3b, v48
	v_exp_f32_e32 v48, v48
	v_add_f32_e32 v38, v161, v38
	v_cndmask_b32_e64 v166, v39, 0, s[82:83]
	v_fma_f32 v39, v64, s78, -v242
	v_cndmask_b32_e64 v167, v48, 0, s[84:85]
	v_mul_f32_e32 v39, 0x3fb8aa3b, v39
	v_fma_f32 v48, v65, s78, -v242
	v_exp_f32_e32 v39, v39
	v_mul_f32_e32 v48, 0x3fb8aa3b, v48
	v_exp_f32_e32 v48, v48
	v_add_f32_e32 v38, v164, v38
	v_cndmask_b32_e64 v168, v39, 0, s[40:41]
	v_fma_f32 v39, v66, s78, -v242
	v_cndmask_b32_e64 v169, v48, 0, s[80:81]
	v_mul_f32_e32 v39, 0x3fb8aa3b, v39
	v_fma_f32 v48, v67, s78, -v242
	v_exp_f32_e32 v39, v39
	v_mul_f32_e32 v48, 0x3fb8aa3b, v48
	v_exp_f32_e32 v48, v48
	v_add_f32_e32 v38, v165, v38
	v_cndmask_b32_e64 v170, v39, 0, s[74:75]
	v_fma_f32 v39, v72, s78, -v242
	v_cndmask_b32_e64 v171, v48, 0, s[76:77]
	v_mul_f32_e32 v39, 0x3fb8aa3b, v39
	v_fma_f32 v48, v73, s78, -v242
	v_exp_f32_e32 v39, v39
	v_mul_f32_e32 v48, 0x3fb8aa3b, v48
	v_exp_f32_e32 v48, v48
	v_add_f32_e32 v38, v162, v38
	v_cndmask_b32_e64 v72, v39, 0, s[70:71]
	v_fma_f32 v39, v74, s78, -v242
	v_cndmask_b32_e64 v73, v48, 0, s[72:73]
	v_mul_f32_e32 v39, 0x3fb8aa3b, v39
	v_fma_f32 v48, v75, s78, -v242
	v_exp_f32_e32 v39, v39
	v_mul_f32_e32 v48, 0x3fb8aa3b, v48
	v_exp_f32_e32 v48, v48
	v_add_f32_e32 v38, v163, v38
	v_cndmask_b32_e64 v74, v39, 0, s[66:67]
	v_fma_f32 v39, v68, s78, -v242
	v_add_f32_e32 v38, v166, v38
	v_cndmask_b32_e64 v75, v48, 0, s[68:69]
	v_mul_f32_e32 v39, 0x3fb8aa3b, v39
	v_fma_f32 v48, v69, s78, -v242
	v_add_f32_e32 v38, v167, v38
	v_exp_f32_e32 v39, v39
	v_mul_f32_e32 v48, 0x3fb8aa3b, v48
	v_add_f32_e32 v38, v168, v38
	v_exp_f32_e32 v48, v48
	v_add_f32_e32 v38, v169, v38
	v_add_f32_e32 v38, v170, v38
	v_add_f32_e32 v38, v171, v38
	v_cndmask_b32_e64 v68, v39, 0, s[62:63]
	v_fma_f32 v39, v70, s78, -v242
	v_add_f32_e32 v38, v72, v38
	v_cndmask_b32_e64 v69, v48, 0, s[64:65]
	v_mul_f32_e32 v39, 0x3fb8aa3b, v39
	v_fma_f32 v48, v71, s78, -v242
	v_add_f32_e32 v38, v73, v38
	v_exp_f32_e32 v39, v39
	v_mul_f32_e32 v48, 0x3fb8aa3b, v48
	v_add_f32_e32 v38, v74, v38
	v_exp_f32_e32 v48, v48
	v_add_f32_e32 v38, v75, v38
	v_add_f32_e32 v38, v68, v38
	v_add_f32_e32 v38, v69, v38
	v_cndmask_b32_e64 v70, v39, 0, s[58:59]
	v_add_f32_e32 v38, v70, v38
	v_cndmask_b32_e64 v71, v48, 0, s[60:61]
	v_add_f32_e32 v48, v71, v38
	ds_bpermute_b32 v49, v241, v48
	v_lshl_add_u32 v46, v44, 10, v252
	v_lshl_add_u32 v76, v45, 10, v252
	v_lshl_add_u32 v38, v122, 10, v252
	s_waitcnt lgkmcnt(0)
	v_add_f32_e32 v50, v48, v49
	v_lshl_add_u32 v48, v123, 10, v252
	v_lshl_add_u32 v40, v43, 10, v252
	v_mov_b32_e32 v84, v82
	global_load_dwordx4 v[24:27], v24, s[100:101]
	global_load_dwordx4 v[40:43], v40, s[100:101]
	global_load_dwordx4 v[44:47], v46, s[100:101]
	global_load_dwordx4 v[76:79], v76, s[100:101]
	global_load_dwordx4 v[80:83], v80, s[100:101]
	global_load_dwordx4 v[84:87], v84, s[100:101]
	global_load_dwordx4 v[52:55], v38, s[100:101]
	global_load_dwordx4 v[56:59], v48, s[100:101]
	ds_bpermute_b32 v51, v240, v50
	s_waitcnt lgkmcnt(0)
	v_add_f32_e32 v50, v50, v51
	v_div_scale_f32 v51, s[0:1], v50, v50, 1.0
	v_rcp_f32_e32 v60, v51
	s_nop 0
	v_fma_f32 v38, -v51, v60, 1.0
	v_fmac_f32_e32 v60, v38, v60
	v_div_scale_f32 v38, vcc, 1.0, v50, 1.0
	v_mul_f32_e32 v39, v38, v60
	v_fma_f32 v48, -v51, v39, v38
	v_fmac_f32_e32 v39, v48, v60
	v_fma_f32 v38, -v51, v39, v38
	v_div_fmas_f32 v38, v38, v60, v39
	v_div_fixup_f32 v122, v38, v50, 1.0
	v_pk_mul_f32 v[48:49], v[124:125], v[122:123] op_sel_hi:[1,0]
	v_pk_mul_f32 v[50:51], v[148:149], v[122:123] op_sel_hi:[1,0]
	v_pk_mul_f32 v[38:39], v[128:129], v[122:123] op_sel_hi:[1,0]
	v_pk_mul_f32 v[60:61], v[130:131], v[122:123] op_sel_hi:[1,0]
	v_cvt_pk_bf16_f32 v64, v48, v49
	v_cvt_pk_bf16_f32 v65, v38, v39
	v_pk_mul_f32 v[48:49], v[126:127], v[122:123] op_sel_hi:[1,0]
	v_cvt_pk_bf16_f32 v66, v60, v61
	v_cvt_pk_bf16_f32 v67, v50, v51
	v_pk_mul_f32 v[50:51], v[150:151], v[122:123] op_sel_hi:[1,0]
	v_pk_mul_f32 v[62:63], v[146:147], v[122:123] op_sel_hi:[1,0]
	v_pk_mul_f32 v[16:17], v[16:17], v[122:123] op_sel_hi:[1,0]
	v_pk_mul_f32 v[38:39], v[144:145], v[122:123] op_sel_hi:[1,0]
	v_cvt_pk_bf16_f32 v60, v48, v49
	v_pk_mul_f32 v[30:31], v[30:31], v[122:123] op_sel_hi:[1,0]
	v_cvt_pk_bf16_f32 v61, v38, v39
	v_cvt_pk_bf16_f32 v62, v62, v63
	v_cvt_pk_bf16_f32 v63, v50, v51
	v_pk_mul_f32 v[28:29], v[28:29], v[122:123] op_sel_hi:[1,0]
	v_pk_mul_f32 v[18:19], v[18:19], v[122:123] op_sel_hi:[1,0]
	v_cvt_pk_bf16_f32 v48, v28, v29
	v_cvt_pk_bf16_f32 v49, v30, v31
	v_cvt_pk_bf16_f32 v50, v16, v17
	v_pk_mul_f32 v[16:17], v[20:21], v[122:123] op_sel_hi:[1,0]
	v_pk_mul_f32 v[38:39], v[120:121], v[122:123] op_sel_hi:[1,0]
	v_pk_mul_f32 v[20:21], v[36:37], v[122:123] op_sel_hi:[1,0]
	v_cvt_pk_bf16_f32 v51, v38, v39
	v_pk_mul_f32 v[22:23], v[22:23], v[122:123] op_sel_hi:[1,0]
	v_cvt_pk_bf16_f32 v36, v18, v19
	v_cvt_pk_bf16_f32 v37, v16, v17
	v_pk_mul_f32 v[16:17], v[34:35], v[122:123] op_sel_hi:[1,0]
	v_pk_mul_f32 v[18:19], v[32:33], v[122:123] op_sel_hi:[1,0]
	v_cvt_pk_bf16_f32 v38, v22, v23
	v_cvt_pk_bf16_f32 v39, v20, v21
	v_pk_mul_f32 v[20:21], v[156:157], v[122:123] op_sel_hi:[1,0]
	v_pk_mul_f32 v[22:23], v[152:153], v[122:123] op_sel_hi:[1,0]
	v_cvt_pk_bf16_f32 v32, v18, v19
	v_cvt_pk_bf16_f32 v33, v16, v17
	v_pk_mul_f32 v[16:17], v[158:159], v[122:123] op_sel_hi:[1,0]
	v_pk_mul_f32 v[18:19], v[154:155], v[122:123] op_sel_hi:[1,0]
	v_cvt_pk_bf16_f32 v34, v22, v23
	v_cvt_pk_bf16_f32 v35, v20, v21
	v_pk_mul_f32 v[20:21], v[164:165], v[122:123] op_sel_hi:[1,0]
	v_pk_mul_f32 v[22:23], v[160:161], v[122:123] op_sel_hi:[1,0]
	v_cvt_pk_bf16_f32 v28, v18, v19
	v_cvt_pk_bf16_f32 v29, v16, v17
	v_pk_mul_f32 v[16:17], v[166:167], v[122:123] op_sel_hi:[1,0]
	v_pk_mul_f32 v[18:19], v[162:163], v[122:123] op_sel_hi:[1,0]
	v_cvt_pk_bf16_f32 v30, v22, v23
	v_cvt_pk_bf16_f32 v31, v20, v21
	v_pk_mul_f32 v[120:121], v[170:171], v[122:123] op_sel_hi:[1,0]
	v_pk_mul_f32 v[22:23], v[168:169], v[122:123] op_sel_hi:[1,0]
	v_cvt_pk_bf16_f32 v20, v18, v19
	v_cvt_pk_bf16_f32 v21, v16, v17
	v_pk_mul_f32 v[18:19], v[74:75], v[122:123] op_sel_hi:[1,0]
	v_pk_mul_f32 v[16:17], v[72:73], v[122:123] op_sel_hi:[1,0]
	v_cvt_pk_bf16_f32 v22, v22, v23
	v_cvt_pk_bf16_f32 v23, v120, v121
	v_pk_mul_f32 v[70:71], v[70:71], v[122:123] op_sel_hi:[1,0]
	v_pk_mul_f32 v[68:69], v[68:69], v[122:123] op_sel_hi:[1,0]
	v_cvt_pk_bf16_f32 v16, v16, v17
	v_cvt_pk_bf16_f32 v17, v18, v19
	s_nop 0
	v_cvt_pk_bf16_f32 v18, v68, v69
	v_cvt_pk_bf16_f32 v19, v70, v71
	ds_read_b128 v[120:123], v182 offset:64
	ds_read_b128 v[124:127], v182 offset:80
	s_waitcnt lgkmcnt(1)
; #define LAS __attribute__((address_space(3)))
; #define ATT_FENCE() asm volatile("" ::: "memory")
; #define ATT_PV(nt_, ra_, rb_) acc[nt_] = __builtin_amdgcn_mfma_f32_16x16x32_bf16(pa[ch], __builtin_bit_cast(bf16x8, (v4u){ra_.x, ra_.y, rb_.x, rb_.y}), acc[nt_], 0, 0, 0)
; DI void attn_worker(unsigned char* ws, LAS unsigned char* lds, LAS unsigned* qctr, int wave) {
;     ...
;         for (int ch = 0; ch < 8; ++ch) {
;             if (ch + 2 < 8) { const int c2 = (ch + 2) % 3;
;                 ix[c2][0] = *(const LAS v4i*)(idl + 64 * kg + 8 * (ch + 2)); ix[c2][1] = *(const LAS v4i*)(idl + 64 * kg + 8 * (ch + 2) + 4);
; #pragma unroll
;                 for (int j = 0; j < 8; ++j) vv[c2][j] = *(const v4u*)(vbase + (size_t)ix[c2][j >> 2][j & 3] * KVD);
;                 ATT_FENCE(); }
; #pragma unroll
;             for (int j = 0; j < 8; ++j) *(LAS v4u*)(size_t)(vwb[j >> 2] + 64 * j) = vv[ch % 3][j];
;             v2u r0, r1, r2, r3, r4, r5, r6, r7, r8, r9, r10, r11, r12, r13, r14, r15;
;             asm volatile("ds_read_b64_tr_b16 %0, %16\n\tds_read_b64_tr_b16 %1, %18\n\tds_read_b64_tr_b16 %2, %17\n\tds_read_b64_tr_b16 %3, %19\n\t"
;                          "ds_read_b64_tr_b16 %4, %16 offset:512\n\tds_read_b64_tr_b16 %5, %18 offset:512\n\tds_read_b64_tr_b16 %6, %17 offset:512\n\tds_read_b64_tr_b16 %7, %19 offset:512\n\t"
;                          "ds_read_b64_tr_b16 %8, %16 offset:1024\n\tds_read_b64_tr_b16 %9, %18 offset:1024\n\tds_read_b64_tr_b16 %10, %17 offset:1024\n\tds_read_b64_tr_b16 %11, %19 offset:1024\n\t"
;                          "ds_read_b64_tr_b16 %12, %16 offset:1536\n\tds_read_b64_tr_b16 %13, %18 offset:1536\n\tds_read_b64_tr_b16 %14, %17 offset:1536\n\tds_read_b64_tr_b16 %15, %19 offset:1536\n\ts_waitcnt lgkmcnt(0)"
;                          : "=&v"(r0), "=&v"(r1), "=&v"(r2), "=&v"(r3), "=&v"(r4), "=&v"(r5), "=&v"(r6), "=&v"(r7), "=&v"(r8), "=&v"(r9), "=&v"(r10), "=&v"(r11), "=&v"(r12), "=&v"(r13), "=&v"(r14), "=&v"(r15)
;                          : "v"(vtb[0][0]), "v"(vtb[0][1]), "v"(vtb[1][0]), "v"(vtb[1][1]) : "memory");
;     ...
;             ATT_PV(0, r0, r1); ATT_PV(1, r2, r3); ATT_PV(2, r4, r5); ATT_PV(3, r6, r7); ATT_PV(4, r8, r9); ATT_PV(5, r10, r11); ATT_PV(6, r12, r13); ATT_PV(7, r14, r15);
	v_lshl_add_u32 v68, v120, 10, v252
	v_lshl_add_u32 v70, v121, 10, v252
	v_lshl_add_u32 v120, v122, 10, v252
	v_lshl_add_u32 v128, v123, 10, v252
	s_waitcnt lgkmcnt(0)
	v_lshl_add_u32 v144, v124, 10, v252
	v_lshl_add_u32 v146, v125, 10, v252
	v_mov_b32_e32 v124, v146
	v_mov_b32_e32 v72, v70
	global_load_dwordx4 v[68:71], v68, s[100:101]
	global_load_dwordx4 v[72:75], v72, s[100:101]
	global_load_dwordx4 v[120:123], v120, s[100:101]
	global_load_dwordx4 v[128:131], v128, s[100:101]
	global_load_dwordx4 v[144:147], v144, s[100:101]
	global_load_dwordx4 v[148:151], v124, s[100:101]
	v_lshl_add_u32 v124, v126, 10, v252
	v_lshl_add_u32 v152, v127, 10, v252
	global_load_dwordx4 v[124:127], v124, s[100:101]
	global_load_dwordx4 v[152:155], v152, s[100:101]
	s_waitcnt vmcnt(23)
	ds_write_b128 v236, v[88:91]
	s_waitcnt vmcnt(22)
	ds_write_b128 v236, v[92:95] offset:64
	s_waitcnt vmcnt(21)
	ds_write_b128 v236, v[96:99] offset:128
	s_waitcnt vmcnt(20)
	ds_write_b128 v236, v[100:103] offset:192
	s_waitcnt vmcnt(19)
	ds_write_b128 v237, v[104:107] offset:256
	s_waitcnt vmcnt(18)
	ds_write_b128 v237, v[108:111] offset:320
	s_waitcnt vmcnt(17)
	ds_write_b128 v237, v[112:115] offset:384
	s_waitcnt vmcnt(16)
	ds_write_b128 v237, v[116:119] offset:448
	ds_read_b64_tr_b16 v[116:117], v176
	ds_read_b64_tr_b16 v[118:119], v178
	ds_read_b64_tr_b16 v[112:113], v177
	ds_read_b64_tr_b16 v[114:115], v179
	ds_read_b64_tr_b16 v[108:109], v176 offset:512
	ds_read_b64_tr_b16 v[110:111], v178 offset:512
	ds_read_b64_tr_b16 v[104:105], v177 offset:512
	ds_read_b64_tr_b16 v[106:107], v179 offset:512
	ds_read_b64_tr_b16 v[100:101], v176 offset:1024
	ds_read_b64_tr_b16 v[102:103], v178 offset:1024
	ds_read_b64_tr_b16 v[96:97], v177 offset:1024
	ds_read_b64_tr_b16 v[98:99], v179 offset:1024
	ds_read_b64_tr_b16 v[92:93], v176 offset:1536
	ds_read_b64_tr_b16 v[94:95], v178 offset:1536
	ds_read_b64_tr_b16 v[88:89], v177 offset:1536
	ds_read_b64_tr_b16 v[90:91], v179 offset:1536
	s_waitcnt lgkmcnt(0)
	ds_read_b128 v[156:159], v182 offset:96
	ds_read_b128 v[164:167], v182 offset:112
	v_mfma_f32_16x16x32_bf16 v[116:119], v[64:67], v[116:119], 0
	s_waitcnt lgkmcnt(1)
	v_mfma_f32_16x16x32_bf16 v[112:115], v[64:67], v[112:115], 0
	v_lshl_add_u32 v168, v159, 10, v252
	s_waitcnt lgkmcnt(0)
	v_lshl_add_u32 v240, v164, 10, v252
	v_mfma_f32_16x16x32_bf16 v[108:111], v[64:67], v[108:111], 0
	v_lshl_add_u32 v242, v165, 10, v252
	v_mfma_f32_16x16x32_bf16 v[104:107], v[64:67], v[104:107], 0
	v_mov_b32_e32 v164, v242
	v_mfma_f32_16x16x32_bf16 v[100:103], v[64:67], v[100:103], 0
	v_lshl_add_u32 v248, v167, 10, v252
	v_mfma_f32_16x16x32_bf16 v[96:99], v[64:67], v[96:99], 0
	v_mfma_f32_16x16x32_bf16 v[92:95], v[64:67], v[92:95], 0
	v_mfma_f32_16x16x32_bf16 v[160:163], v[64:67], v[88:91], 0
	v_lshl_add_u32 v64, v156, 10, v252
	v_lshl_add_u32 v66, v157, 10, v252
	v_lshl_add_u32 v156, v158, 10, v252
	v_mov_b32_e32 v88, v66
	global_load_dwordx4 v[64:67], v64, s[100:101]
	global_load_dwordx4 v[88:91], v88, s[100:101]
	global_load_dwordx4 v[156:159], v156, s[100:101]
	global_load_dwordx4 v[168:171], v168, s[100:101]
	global_load_dwordx4 v[240:243], v240, s[100:101]
	global_load_dwordx4 v[244:247], v164, s[100:101]
	v_lshl_add_u32 v164, v166, 10, v252
	global_load_dwordx4 v[164:167], v164, s[100:101]
	global_load_dwordx4 v[248:251], v248, s[100:101]
	s_waitcnt vmcnt(23)
	ds_write_b128 v236, v[24:27]
	s_waitcnt vmcnt(22)
	ds_write_b128 v236, v[40:43] offset:64
	s_waitcnt vmcnt(21)
	ds_write_b128 v236, v[44:47] offset:128
	s_waitcnt vmcnt(20)
	ds_write_b128 v236, v[76:79] offset:192
	s_waitcnt vmcnt(19)
	ds_write_b128 v237, v[80:83] offset:256
	s_waitcnt vmcnt(18)
	ds_write_b128 v237, v[84:87] offset:320
	s_waitcnt vmcnt(17)
	ds_write_b128 v237, v[52:55] offset:384
	s_waitcnt vmcnt(16)
	ds_write_b128 v237, v[56:59] offset:448
	ds_read_b64_tr_b16 v[84:85], v176
	ds_read_b64_tr_b16 v[86:87], v178
	ds_read_b64_tr_b16 v[80:81], v177
	ds_read_b64_tr_b16 v[82:83], v179
	ds_read_b64_tr_b16 v[76:77], v176 offset:512
	ds_read_b64_tr_b16 v[78:79], v178 offset:512
	ds_read_b64_tr_b16 v[56:57], v177 offset:512
	ds_read_b64_tr_b16 v[58:59], v179 offset:512
	ds_read_b64_tr_b16 v[52:53], v176 offset:1024
	ds_read_b64_tr_b16 v[54:55], v178 offset:1024
	ds_read_b64_tr_b16 v[44:45], v177 offset:1024
	ds_read_b64_tr_b16 v[46:47], v179 offset:1024
	ds_read_b64_tr_b16 v[40:41], v176 offset:1536
	ds_read_b64_tr_b16 v[42:43], v178 offset:1536
	ds_read_b64_tr_b16 v[24:25], v177 offset:1536
	ds_read_b64_tr_b16 v[26:27], v179 offset:1536
	s_waitcnt lgkmcnt(0)
	s_nop 0
	v_mfma_f32_16x16x32_bf16 v[52:55], v[60:63], v[52:55], v[100:103]
	v_mfma_f32_16x16x32_bf16 v[44:47], v[60:63], v[44:47], v[96:99]
	s_nop 1
	ds_read_b128 v[100:103], v182 offset:144
	ds_read_b128 v[96:99], v182 offset:128
	v_mfma_f32_16x16x32_bf16 v[84:87], v[60:63], v[84:87], v[116:119]
	v_mfma_f32_16x16x32_bf16 v[80:83], v[60:63], v[80:83], v[112:115]
	s_waitcnt lgkmcnt(1)
	s_nop 0
	v_lshl_add_u32 v116, v103, 10, v252
	v_mfma_f32_16x16x32_bf16 v[76:79], v[60:63], v[76:79], v[108:111]
	v_mfma_f32_16x16x32_bf16 v[56:59], v[60:63], v[56:59], v[104:107]
	s_nop 1
	v_lshl_add_u32 v108, v100, 10, v252
	v_mfma_f32_16x16x32_bf16 v[92:95], v[60:63], v[40:43], v[92:95]
	s_waitcnt lgkmcnt(0)
	v_lshl_add_u32 v104, v99, 10, v252
	v_lshl_add_u32 v110, v101, 10, v252
	v_mfma_f32_16x16x32_bf16 v[60:63], v[60:63], v[24:27], v[160:163]
	v_lshl_add_u32 v24, v96, 10, v252
	v_lshl_add_u32 v26, v97, 10, v252
	v_lshl_add_u32 v96, v98, 10, v252
	v_mov_b32_e32 v100, v110
	v_mov_b32_e32 v40, v26
	global_load_dwordx4 v[24:27], v24, s[100:101]
	global_load_dwordx4 v[40:43], v40, s[100:101]
	global_load_dwordx4 v[96:99], v96, s[100:101]
	global_load_dwordx4 v[104:107], v104, s[100:101]
	global_load_dwordx4 v[108:111], v108, s[100:101]
	global_load_dwordx4 v[112:115], v100, s[100:101]
	v_lshl_add_u32 v100, v102, 10, v252
	global_load_dwordx4 v[100:103], v100, s[100:101]
	global_load_dwordx4 v[116:119], v116, s[100:101]
	s_waitcnt vmcnt(23)
; #define LAS __attribute__((address_space(3)))
; #define ATT_FENCE() asm volatile("" ::: "memory")
; #define ATT_PV(nt_, ra_, rb_) acc[nt_] = __builtin_amdgcn_mfma_f32_16x16x32_bf16(pa[ch], __builtin_bit_cast(bf16x8, (v4u){ra_.x, ra_.y, rb_.x, rb_.y}), acc[nt_], 0, 0, 0)
; DI void attn_worker(unsigned char* ws, LAS unsigned char* lds, LAS unsigned* qctr, int wave) {
;     ...
;         for (int ch = 0; ch < 8; ++ch) {
;             if (ch + 2 < 8) { const int c2 = (ch + 2) % 3;
;                 ix[c2][0] = *(const LAS v4i*)(idl + 64 * kg + 8 * (ch + 2)); ix[c2][1] = *(const LAS v4i*)(idl + 64 * kg + 8 * (ch + 2) + 4);
; #pragma unroll
;                 for (int j = 0; j < 8; ++j) vv[c2][j] = *(const v4u*)(vbase + (size_t)ix[c2][j >> 2][j & 3] * KVD);
;                 ATT_FENCE(); }
; #pragma unroll
;             for (int j = 0; j < 8; ++j) *(LAS v4u*)(size_t)(vwb[j >> 2] + 64 * j) = vv[ch % 3][j];
;             v2u r0, r1, r2, r3, r4, r5, r6, r7, r8, r9, r10, r11, r12, r13, r14, r15;
;             asm volatile("ds_read_b64_tr_b16 %0, %16\n\tds_read_b64_tr_b16 %1, %18\n\tds_read_b64_tr_b16 %2, %17\n\tds_read_b64_tr_b16 %3, %19\n\t"
;                          "ds_read_b64_tr_b16 %4, %16 offset:512\n\tds_read_b64_tr_b16 %5, %18 offset:512\n\tds_read_b64_tr_b16 %6, %17 offset:512\n\tds_read_b64_tr_b16 %7, %19 offset:512\n\t"
;                          "ds_read_b64_tr_b16 %8, %16 offset:1024\n\tds_read_b64_tr_b16 %9, %18 offset:1024\n\tds_read_b64_tr_b16 %10, %17 offset:1024\n\tds_read_b64_tr_b16 %11, %19 offset:1024\n\t"
;                          "ds_read_b64_tr_b16 %12, %16 offset:1536\n\tds_read_b64_tr_b16 %13, %18 offset:1536\n\tds_read_b64_tr_b16 %14, %17 offset:1536\n\tds_read_b64_tr_b16 %15, %19 offset:1536\n\ts_waitcnt lgkmcnt(0)"
;                          : "=&v"(r0), "=&v"(r1), "=&v"(r2), "=&v"(r3), "=&v"(r4), "=&v"(r5), "=&v"(r6), "=&v"(r7), "=&v"(r8), "=&v"(r9), "=&v"(r10), "=&v"(r11), "=&v"(r12), "=&v"(r13), "=&v"(r14), "=&v"(r15)
;                          : "v"(vtb[0][0]), "v"(vtb[0][1]), "v"(vtb[1][0]), "v"(vtb[1][1]) : "memory");
;     ...
;             ATT_PV(0, r0, r1); ATT_PV(1, r2, r3); ATT_PV(2, r4, r5); ATT_PV(3, r6, r7); ATT_PV(4, r8, r9); ATT_PV(5, r10, r11); ATT_PV(6, r12, r13); ATT_PV(7, r14, r15);
	ds_write_b128 v236, v[68:71]
	s_waitcnt vmcnt(22)
	ds_write_b128 v236, v[72:75] offset:64
	s_waitcnt vmcnt(21)
	ds_write_b128 v236, v[120:123] offset:128
	s_waitcnt vmcnt(20)
	ds_write_b128 v236, v[128:131] offset:192
	s_waitcnt vmcnt(19)
	ds_write_b128 v237, v[144:147] offset:256
	s_waitcnt vmcnt(18)
	ds_write_b128 v237, v[148:151] offset:320
	s_waitcnt vmcnt(17)
	ds_write_b128 v237, v[124:127] offset:384
	s_waitcnt vmcnt(16)
	ds_write_b128 v237, v[152:155] offset:448
	ds_read_b64_tr_b16 v[152:153], v176
	ds_read_b64_tr_b16 v[154:155], v178
	ds_read_b64_tr_b16 v[148:149], v177
	ds_read_b64_tr_b16 v[150:151], v179
	ds_read_b64_tr_b16 v[144:145], v176 offset:512
	ds_read_b64_tr_b16 v[146:147], v178 offset:512
	ds_read_b64_tr_b16 v[128:129], v177 offset:512
	ds_read_b64_tr_b16 v[130:131], v179 offset:512
	ds_read_b64_tr_b16 v[124:125], v176 offset:1024
	ds_read_b64_tr_b16 v[126:127], v178 offset:1024
	ds_read_b64_tr_b16 v[120:121], v177 offset:1024
	ds_read_b64_tr_b16 v[122:123], v179 offset:1024
	ds_read_b64_tr_b16 v[72:73], v176 offset:1536
	ds_read_b64_tr_b16 v[74:75], v178 offset:1536
	ds_read_b64_tr_b16 v[68:69], v177 offset:1536
	ds_read_b64_tr_b16 v[70:71], v179 offset:1536
	s_waitcnt lgkmcnt(0)
	s_nop 0
	v_mfma_f32_16x16x32_bf16 v[72:75], v[48:51], v[72:75], v[92:95]
	s_nop 2
	ds_read_b128 v[92:95], v182 offset:160
	v_mfma_f32_16x16x32_bf16 v[60:63], v[48:51], v[68:71], v[60:63]
	ds_read_b128 v[68:71], v182 offset:176
	v_mfma_f32_16x16x32_bf16 v[56:59], v[48:51], v[128:131], v[56:59]
	s_waitcnt lgkmcnt(0)
	v_lshl_add_u32 v128, v68, 10, v252
	v_mfma_f32_16x16x32_bf16 v[52:55], v[48:51], v[124:127], v[52:55]
	v_lshl_add_u32 v124, v95, 10, v252
	v_mfma_f32_16x16x32_bf16 v[120:123], v[48:51], v[120:123], v[44:47]
	v_lshl_add_u32 v130, v69, 10, v252
	v_mov_b32_e32 v68, v130
	v_lshl_add_u32 v44, v92, 10, v252
	v_lshl_add_u32 v46, v93, 10, v252
	v_lshl_add_u32 v92, v94, 10, v252
	v_mfma_f32_16x16x32_bf16 v[84:87], v[48:51], v[152:155], v[84:87]
	v_mfma_f32_16x16x32_bf16 v[80:83], v[48:51], v[148:151], v[80:83]
	v_mfma_f32_16x16x32_bf16 v[76:79], v[48:51], v[144:147], v[76:79]
	v_mov_b32_e32 v48, v46
	global_load_dwordx4 v[44:47], v44, s[100:101]
	global_load_dwordx4 v[48:51], v48, s[100:101]
	global_load_dwordx4 v[92:95], v92, s[100:101]
	global_load_dwordx4 v[124:127], v124, s[100:101]
	global_load_dwordx4 v[128:131], v128, s[100:101]
	global_load_dwordx4 v[144:147], v68, s[100:101]
	v_lshl_add_u32 v68, v70, 10, v252
	v_lshl_add_u32 v148, v71, 10, v252
	global_load_dwordx4 v[68:71], v68, s[100:101]
	global_load_dwordx4 v[148:151], v148, s[100:101]
	s_waitcnt vmcnt(23)
	ds_write_b128 v236, v[64:67]
	s_waitcnt vmcnt(22)
	ds_write_b128 v236, v[88:91] offset:64
	s_waitcnt vmcnt(21)
	ds_write_b128 v236, v[156:159] offset:128
	s_waitcnt vmcnt(20)
	ds_write_b128 v236, v[168:171] offset:192
	s_waitcnt vmcnt(19)
	ds_write_b128 v237, v[240:243] offset:256
	s_waitcnt vmcnt(18)
	ds_write_b128 v237, v[244:247] offset:320
	s_waitcnt vmcnt(17)
	ds_write_b128 v237, v[164:167] offset:384
	s_waitcnt vmcnt(16)
	ds_write_b128 v237, v[248:251] offset:448
	ds_read_b64_tr_b16 v[240:241], v176
	ds_read_b64_tr_b16 v[242:243], v178
	ds_read_b64_tr_b16 v[168:169], v177
	ds_read_b64_tr_b16 v[170:171], v179
	ds_read_b64_tr_b16 v[164:165], v176 offset:512
	ds_read_b64_tr_b16 v[166:167], v178 offset:512
	ds_read_b64_tr_b16 v[160:161], v177 offset:512
	ds_read_b64_tr_b16 v[162:163], v179 offset:512
	ds_read_b64_tr_b16 v[156:157], v176 offset:1024
	ds_read_b64_tr_b16 v[158:159], v178 offset:1024
	ds_read_b64_tr_b16 v[152:153], v177 offset:1024
	ds_read_b64_tr_b16 v[154:155], v179 offset:1024
	ds_read_b64_tr_b16 v[88:89], v176 offset:1536
	ds_read_b64_tr_b16 v[90:91], v178 offset:1536
	ds_read_b64_tr_b16 v[64:65], v177 offset:1536
	ds_read_b64_tr_b16 v[66:67], v179 offset:1536
	s_waitcnt lgkmcnt(0)
	s_nop 0
	v_mfma_f32_16x16x32_bf16 v[72:75], v[36:39], v[88:91], v[72:75]
	ds_read_b128 v[88:91], v182 offset:192
	v_mfma_f32_16x16x32_bf16 v[84:87], v[36:39], v[240:243], v[84:87]
	v_mfma_f32_16x16x32_bf16 v[80:83], v[36:39], v[168:171], v[80:83]
	v_mfma_f32_16x16x32_bf16 v[76:79], v[36:39], v[164:167], v[76:79]
	v_mfma_f32_16x16x32_bf16 v[56:59], v[36:39], v[160:163], v[56:59]
	v_mfma_f32_16x16x32_bf16 v[52:55], v[36:39], v[156:159], v[52:55]
	v_mfma_f32_16x16x32_bf16 v[120:123], v[36:39], v[152:155], v[120:123]
	v_mfma_f32_16x16x32_bf16 v[36:39], v[36:39], v[64:67], v[60:63]
	s_nop 2
	ds_read_b128 v[60:63], v182 offset:208
	s_waitcnt lgkmcnt(1)
	v_lshl_add_u32 v64, v88, 10, v252
	v_lshl_add_u32 v88, v89, 10, v252
	global_load_dwordx4 v[64:67], v64, s[100:101]
	global_load_dwordx4 v[152:155], v88, s[100:101]
	v_lshl_add_u32 v88, v90, 10, v252
	v_lshl_add_u32 v156, v91, 10, v252
	s_waitcnt lgkmcnt(0)
	v_lshl_add_u32 v160, v60, 10, v252
	v_lshl_add_u32 v162, v61, 10, v252
	v_mov_b32_e32 v60, v162
	global_load_dwordx4 v[88:91], v88, s[100:101]
	global_load_dwordx4 v[156:159], v156, s[100:101]
	global_load_dwordx4 v[160:163], v160, s[100:101]
	global_load_dwordx4 v[164:167], v60, s[100:101]
	v_lshl_add_u32 v60, v62, 10, v252
	v_lshl_add_u32 v168, v63, 10, v252
	global_load_dwordx4 v[60:63], v60, s[100:101]
	global_load_dwordx4 v[168:171], v168, s[100:101]
	s_waitcnt vmcnt(23)
	ds_write_b128 v236, v[24:27]
	s_waitcnt vmcnt(22)
	ds_write_b128 v236, v[40:43] offset:64
	s_waitcnt vmcnt(21)
	ds_write_b128 v236, v[96:99] offset:128
	s_waitcnt vmcnt(20)
	ds_write_b128 v236, v[104:107] offset:192
	s_waitcnt vmcnt(19)
	ds_write_b128 v237, v[108:111] offset:256
	s_waitcnt vmcnt(18)
	ds_write_b128 v237, v[112:115] offset:320
	s_waitcnt vmcnt(17)
	ds_write_b128 v237, v[100:103] offset:384
	s_waitcnt vmcnt(16)
; #define LAS __attribute__((address_space(3)))
; #define ATT_FENCE() asm volatile("" ::: "memory")
; #define ATT_PV(nt_, ra_, rb_) acc[nt_] = __builtin_amdgcn_mfma_f32_16x16x32_bf16(pa[ch], __builtin_bit_cast(bf16x8, (v4u){ra_.x, ra_.y, rb_.x, rb_.y}), acc[nt_], 0, 0, 0)
; DI void attn_worker(unsigned char* ws, LAS unsigned char* lds, LAS unsigned* qctr, int wave) {
;     ...
;         for (int ch = 0; ch < 8; ++ch) {
;             if (ch + 2 < 8) { const int c2 = (ch + 2) % 3;
;                 ix[c2][0] = *(const LAS v4i*)(idl + 64 * kg + 8 * (ch + 2)); ix[c2][1] = *(const LAS v4i*)(idl + 64 * kg + 8 * (ch + 2) + 4);
; #pragma unroll
;                 for (int j = 0; j < 8; ++j) vv[c2][j] = *(const v4u*)(vbase + (size_t)ix[c2][j >> 2][j & 3] * KVD);
;                 ATT_FENCE(); }
; #pragma unroll
;             for (int j = 0; j < 8; ++j) *(LAS v4u*)(size_t)(vwb[j >> 2] + 64 * j) = vv[ch % 3][j];
;             v2u r0, r1, r2, r3, r4, r5, r6, r7, r8, r9, r10, r11, r12, r13, r14, r15;
;             asm volatile("ds_read_b64_tr_b16 %0, %16\n\tds_read_b64_tr_b16 %1, %18\n\tds_read_b64_tr_b16 %2, %17\n\tds_read_b64_tr_b16 %3, %19\n\t"
;                          "ds_read_b64_tr_b16 %4, %16 offset:512\n\tds_read_b64_tr_b16 %5, %18 offset:512\n\tds_read_b64_tr_b16 %6, %17 offset:512\n\tds_read_b64_tr_b16 %7, %19 offset:512\n\t"
;                          "ds_read_b64_tr_b16 %8, %16 offset:1024\n\tds_read_b64_tr_b16 %9, %18 offset:1024\n\tds_read_b64_tr_b16 %10, %17 offset:1024\n\tds_read_b64_tr_b16 %11, %19 offset:1024\n\t"
;                          "ds_read_b64_tr_b16 %12, %16 offset:1536\n\tds_read_b64_tr_b16 %13, %18 offset:1536\n\tds_read_b64_tr_b16 %14, %17 offset:1536\n\tds_read_b64_tr_b16 %15, %19 offset:1536\n\ts_waitcnt lgkmcnt(0)"
;                          : "=&v"(r0), "=&v"(r1), "=&v"(r2), "=&v"(r3), "=&v"(r4), "=&v"(r5), "=&v"(r6), "=&v"(r7), "=&v"(r8), "=&v"(r9), "=&v"(r10), "=&v"(r11), "=&v"(r12), "=&v"(r13), "=&v"(r14), "=&v"(r15)
;                          : "v"(vtb[0][0]), "v"(vtb[0][1]), "v"(vtb[1][0]), "v"(vtb[1][1]) : "memory");
;     ...
;             ATT_PV(0, r0, r1); ATT_PV(1, r2, r3); ATT_PV(2, r4, r5); ATT_PV(3, r6, r7); ATT_PV(4, r8, r9); ATT_PV(5, r10, r11); ATT_PV(6, r12, r13); ATT_PV(7, r14, r15);
	ds_write_b128 v237, v[116:119] offset:448
	ds_read_b64_tr_b16 v[116:117], v176
	ds_read_b64_tr_b16 v[118:119], v178
	ds_read_b64_tr_b16 v[112:113], v177
	ds_read_b64_tr_b16 v[114:115], v179
	ds_read_b64_tr_b16 v[108:109], v176 offset:512
	ds_read_b64_tr_b16 v[110:111], v178 offset:512
	ds_read_b64_tr_b16 v[104:105], v177 offset:512
	ds_read_b64_tr_b16 v[106:107], v179 offset:512
	ds_read_b64_tr_b16 v[100:101], v176 offset:1024
	ds_read_b64_tr_b16 v[102:103], v178 offset:1024
	ds_read_b64_tr_b16 v[96:97], v177 offset:1024
	ds_read_b64_tr_b16 v[98:99], v179 offset:1024
	ds_read_b64_tr_b16 v[40:41], v176 offset:1536
	ds_read_b64_tr_b16 v[42:43], v178 offset:1536
	ds_read_b64_tr_b16 v[24:25], v177 offset:1536
	ds_read_b64_tr_b16 v[26:27], v179 offset:1536
	s_waitcnt lgkmcnt(0)
	s_nop 0
	v_mfma_f32_16x16x32_bf16 v[40:43], v[32:35], v[40:43], v[72:75]
	s_nop 2
	ds_read_b128 v[72:75], v182 offset:224
	v_mfma_f32_16x16x32_bf16 v[84:87], v[32:35], v[116:119], v[84:87]
	v_mfma_f32_16x16x32_bf16 v[80:83], v[32:35], v[112:115], v[80:83]
	v_mfma_f32_16x16x32_bf16 v[76:79], v[32:35], v[108:111], v[76:79]
	v_mfma_f32_16x16x32_bf16 v[56:59], v[32:35], v[104:107], v[56:59]
	v_mfma_f32_16x16x32_bf16 v[52:55], v[32:35], v[100:103], v[52:55]
	v_mfma_f32_16x16x32_bf16 v[96:99], v[32:35], v[96:99], v[120:123]
	v_mfma_f32_16x16x32_bf16 v[24:27], v[32:35], v[24:27], v[36:39]
	ds_read_b128 v[32:35], v182 offset:240
	s_waitcnt lgkmcnt(1)
	v_lshl_add_u32 v104, v75, 10, v252
	v_lshl_add_u32 v36, v72, 10, v252
	v_lshl_add_u32 v72, v73, 10, v252
	global_load_dwordx4 v[36:39], v36, s[100:101]
	global_load_dwordx4 v[100:103], v72, s[100:101]
	v_lshl_add_u32 v72, v74, 10, v252
	s_waitcnt lgkmcnt(0)
	v_lshl_add_u32 v108, v32, 10, v252
	v_lshl_add_u32 v110, v33, 10, v252
	v_mov_b32_e32 v32, v110
	global_load_dwordx4 v[72:75], v72, s[100:101]
	global_load_dwordx4 v[104:107], v104, s[100:101]
	global_load_dwordx4 v[108:111], v108, s[100:101]
	global_load_dwordx4 v[112:115], v32, s[100:101]
	v_lshl_add_u32 v32, v34, 10, v252
	v_lshl_add_u32 v116, v35, 10, v252
	global_load_dwordx4 v[32:35], v32, s[100:101]
	global_load_dwordx4 v[116:119], v116, s[100:101]
	s_waitcnt vmcnt(23)
	ds_write_b128 v236, v[44:47]
	s_waitcnt vmcnt(22)
	ds_write_b128 v236, v[48:51] offset:64
	s_waitcnt vmcnt(21)
	ds_write_b128 v236, v[92:95] offset:128
	s_waitcnt vmcnt(20)
	ds_write_b128 v236, v[124:127] offset:192
	s_waitcnt vmcnt(19)
	ds_write_b128 v237, v[128:131] offset:256
	s_waitcnt vmcnt(18)
	ds_write_b128 v237, v[144:147] offset:320
	s_waitcnt vmcnt(17)
	ds_write_b128 v237, v[68:71] offset:384
	s_waitcnt vmcnt(16)
	ds_write_b128 v237, v[148:151] offset:448
	ds_read_b64_tr_b16 v[144:145], v176
	ds_read_b64_tr_b16 v[146:147], v178
	ds_read_b64_tr_b16 v[128:129], v177
	ds_read_b64_tr_b16 v[130:131], v179
	ds_read_b64_tr_b16 v[124:125], v176 offset:512
	ds_read_b64_tr_b16 v[126:127], v178 offset:512
	ds_read_b64_tr_b16 v[120:121], v177 offset:512
	ds_read_b64_tr_b16 v[122:123], v179 offset:512
	ds_read_b64_tr_b16 v[92:93], v176 offset:1024
	ds_read_b64_tr_b16 v[94:95], v178 offset:1024
	ds_read_b64_tr_b16 v[68:69], v177 offset:1024
	ds_read_b64_tr_b16 v[70:71], v179 offset:1024
	ds_read_b64_tr_b16 v[48:49], v176 offset:1536
	ds_read_b64_tr_b16 v[50:51], v178 offset:1536
	ds_read_b64_tr_b16 v[44:45], v177 offset:1536
	ds_read_b64_tr_b16 v[46:47], v179 offset:1536
	s_waitcnt lgkmcnt(0)
	s_waitcnt vmcnt(15)
	ds_write_b128 v236, v[64:67]
	s_waitcnt vmcnt(14)
	ds_write_b128 v236, v[152:155] offset:64
	s_waitcnt vmcnt(13)
	ds_write_b128 v236, v[88:91] offset:128
	s_waitcnt vmcnt(12)
	ds_write_b128 v236, v[156:159] offset:192
	s_waitcnt vmcnt(11)
	ds_write_b128 v237, v[160:163] offset:256
	s_waitcnt vmcnt(10)
	ds_write_b128 v237, v[164:167] offset:320
	s_waitcnt vmcnt(9)
	ds_write_b128 v237, v[60:63] offset:384
	s_waitcnt vmcnt(8)
	ds_write_b128 v237, v[168:171] offset:448
	v_mfma_f32_16x16x32_bf16 v[84:87], v[28:31], v[144:147], v[84:87]
	v_mfma_f32_16x16x32_bf16 v[80:83], v[28:31], v[128:131], v[80:83]
	v_mfma_f32_16x16x32_bf16 v[76:79], v[28:31], v[124:127], v[76:79]
	v_mfma_f32_16x16x32_bf16 v[56:59], v[28:31], v[120:123], v[56:59]
	v_mfma_f32_16x16x32_bf16 v[52:55], v[28:31], v[92:95], v[52:55]
	v_mfma_f32_16x16x32_bf16 v[68:71], v[28:31], v[68:71], v[96:99]
	v_mfma_f32_16x16x32_bf16 v[40:43], v[28:31], v[48:51], v[40:43]
	v_mfma_f32_16x16x32_bf16 v[24:27], v[28:31], v[44:47], v[24:27]
	ds_read_b64_tr_b16 v[96:97], v176
	ds_read_b64_tr_b16 v[98:99], v178
	ds_read_b64_tr_b16 v[92:93], v177
	ds_read_b64_tr_b16 v[94:95], v179
	ds_read_b64_tr_b16 v[88:89], v176 offset:512
	ds_read_b64_tr_b16 v[90:91], v178 offset:512
	ds_read_b64_tr_b16 v[64:65], v177 offset:512
	ds_read_b64_tr_b16 v[66:67], v179 offset:512
	ds_read_b64_tr_b16 v[60:61], v176 offset:1024
	ds_read_b64_tr_b16 v[62:63], v178 offset:1024
	ds_read_b64_tr_b16 v[48:49], v177 offset:1024
	ds_read_b64_tr_b16 v[50:51], v179 offset:1024
	ds_read_b64_tr_b16 v[44:45], v176 offset:1536
	ds_read_b64_tr_b16 v[46:47], v178 offset:1536
	ds_read_b64_tr_b16 v[28:29], v177 offset:1536
	ds_read_b64_tr_b16 v[30:31], v179 offset:1536
	s_waitcnt lgkmcnt(0)
	s_waitcnt vmcnt(7)
	ds_write_b128 v236, v[36:39]
	s_waitcnt vmcnt(6)
	ds_write_b128 v236, v[100:103] offset:64
	s_waitcnt vmcnt(5)
	ds_write_b128 v236, v[72:75] offset:128
	s_waitcnt vmcnt(4)
	ds_write_b128 v236, v[104:107] offset:192
	s_waitcnt vmcnt(3)
; #define LAS __attribute__((address_space(3)))
; #define ATT_FENCE() asm volatile("" ::: "memory")
; DI void attn_worker(unsigned char* ws, LAS unsigned char* lds, LAS unsigned* qctr, int wave) {
;     ...
;         for (int ch = 0; ch < 8; ++ch) {
;             if (ch + 2 < 8) { const int c2 = (ch + 2) % 3;
;                 ix[c2][0] = *(const LAS v4i*)(idl + 64 * kg + 8 * (ch + 2)); ix[c2][1] = *(const LAS v4i*)(idl + 64 * kg + 8 * (ch + 2) + 4);
; #pragma unroll
;                 for (int j = 0; j < 8; ++j) vv[c2][j] = *(const v4u*)(vbase + (size_t)ix[c2][j >> 2][j & 3] * KVD);
;                 ATT_FENCE(); }
; #pragma unroll
;             for (int j = 0; j < 8; ++j) *(LAS v4u*)(size_t)(vwb[j >> 2] + 64 * j) = vv[ch % 3][j];
;             v2u r0, r1, r2, r3, r4, r5, r6, r7, r8, r9, r10, r11, r12, r13, r14, r15;
;             asm volatile("ds_read_b64_tr_b16 %0, %16\n\tds_read_b64_tr_b16 %1, %18\n\tds_read_b64_tr_b16 %2, %17\n\tds_read_b64_tr_b16 %3, %19\n\t"
;                          "ds_read_b64_tr_b16 %4, %16 offset:512\n\tds_read_b64_tr_b16 %5, %18 offset:512\n\tds_read_b64_tr_b16 %6, %17 offset:512\n\tds_read_b64_tr_b16 %7, %19 offset:512\n\t"
;                          "ds_read_b64_tr_b16 %8, %16 offset:1024\n\tds_read_b64_tr_b16 %9, %18 offset:1024\n\tds_read_b64_tr_b16 %10, %17 offset:1024\n\tds_read_b64_tr_b16 %11, %19 offset:1024\n\t"
;                          "ds_read_b64_tr_b16 %12, %16 offset:1536\n\tds_read_b64_tr_b16 %13, %18 offset:1536\n\tds_read_b64_tr_b16 %14, %17 offset:1536\n\tds_read_b64_tr_b16 %15, %19 offset:1536\n\ts_waitcnt lgkmcnt(0)"
;                          : "=&v"(r0), "=&v"(r1), "=&v"(r2), "=&v"(r3), "=&v"(r4), "=&v"(r5), "=&v"(r6), "=&v"(r7), "=&v"(r8), "=&v"(r9), "=&v"(r10), "=&v"(r11), "=&v"(r12), "=&v"(r13), "=&v"(r14), "=&v"(r15)
;                          : "v"(vtb[0][0]), "v"(vtb[0][1]), "v"(vtb[1][0]), "v"(vtb[1][1]) : "memory");
;     ...
;             ATT_PV(0, r0, r1); ATT_PV(1, r2, r3); ATT_PV(2, r4, r5); ATT_PV(3, r6, r7); ATT_PV(4, r8, r9); ATT_PV(5, r10, r11); ATT_PV(6, r12, r13); ATT_PV(7, r14, r15);
;     ...
;         }
;         { LAS unsigned short* ob = (LAS unsigned short*)(lds + 2048);
;           if (lane < 16) {
; #pragma unroll
;             for (int nt = 0; nt < 8; ++nt)
; #pragma unroll
;                 for (int e = 0; e < 4; ++e) ob[e * 128 + 16 * nt + lane] = f2bf(acc[nt][e]); }
	ds_write_b128 v237, v[108:111] offset:256
	s_waitcnt vmcnt(2)
	ds_write_b128 v237, v[112:115] offset:320
	s_waitcnt vmcnt(1)
	ds_write_b128 v237, v[32:35] offset:384
	s_waitcnt vmcnt(0)
	ds_write_b128 v237, v[116:119] offset:448
	v_mfma_f32_16x16x32_bf16 v[84:87], v[20:23], v[96:99], v[84:87]
	v_mfma_f32_16x16x32_bf16 v[80:83], v[20:23], v[92:95], v[80:83]
	v_mfma_f32_16x16x32_bf16 v[76:79], v[20:23], v[88:91], v[76:79]
	v_mfma_f32_16x16x32_bf16 v[56:59], v[20:23], v[64:67], v[56:59]
	v_mfma_f32_16x16x32_bf16 v[52:55], v[20:23], v[60:63], v[52:55]
	v_mfma_f32_16x16x32_bf16 v[48:51], v[20:23], v[48:51], v[68:71]
	v_mfma_f32_16x16x32_bf16 v[60:63], v[20:23], v[44:47], v[40:43]
	v_mfma_f32_16x16x32_bf16 v[64:67], v[20:23], v[28:31], v[24:27]
	ds_read_b64_tr_b16 v[44:45], v176
	ds_read_b64_tr_b16 v[46:47], v178
	ds_read_b64_tr_b16 v[40:41], v177
	ds_read_b64_tr_b16 v[42:43], v179
	ds_read_b64_tr_b16 v[36:37], v176 offset:512
	ds_read_b64_tr_b16 v[38:39], v178 offset:512
	ds_read_b64_tr_b16 v[32:33], v177 offset:512
	ds_read_b64_tr_b16 v[34:35], v179 offset:512
	ds_read_b64_tr_b16 v[28:29], v176 offset:1024
	ds_read_b64_tr_b16 v[30:31], v178 offset:1024
	ds_read_b64_tr_b16 v[24:25], v177 offset:1024
	ds_read_b64_tr_b16 v[26:27], v179 offset:1024
	ds_read_b64_tr_b16 v[20:21], v176 offset:1536
	ds_read_b64_tr_b16 v[22:23], v178 offset:1536
	ds_read_b64_tr_b16 v[68:69], v177 offset:1536
	ds_read_b64_tr_b16 v[70:71], v179 offset:1536
	s_waitcnt lgkmcnt(0)
	s_nop 0
	v_mfma_f32_16x16x32_bf16 v[44:47], v[16:19], v[44:47], v[84:87]
	v_mfma_f32_16x16x32_bf16 v[40:43], v[16:19], v[40:43], v[80:83]
	v_mfma_f32_16x16x32_bf16 v[36:39], v[16:19], v[36:39], v[76:79]
	v_mfma_f32_16x16x32_bf16 v[32:35], v[16:19], v[32:35], v[56:59]
	v_mfma_f32_16x16x32_bf16 v[28:31], v[16:19], v[28:31], v[52:55]
	v_mfma_f32_16x16x32_bf16 v[24:27], v[16:19], v[24:27], v[48:51]
	v_mfma_f32_16x16x32_bf16 v[20:23], v[16:19], v[20:23], v[60:63]
	v_mfma_f32_16x16x32_bf16 v[16:19], v[16:19], v[68:71], v[64:67]
	s_mov_b64 s[0:1], exec
	v_readlane_b32 s2, v253, 5
	v_readlane_b32 s3, v253, 6
	s_and_b64 s[2:3], s[0:1], s[2:3]
	s_mov_b64 exec, s[2:3]
	s_cbranch_execz .LBB0_2273
	v_bfe_u32 v48, v44, 16, 1
	v_add3_u32 v44, v44, v48, s79
	ds_write_b16_d16_hi v238, v44 offset:2048
	v_bfe_u32 v44, v45, 16, 1
	v_add3_u32 v44, v45, v44, s79
	ds_write_b16_d16_hi v238, v44 offset:2304
	v_bfe_u32 v44, v46, 16, 1
	v_add3_u32 v44, v46, v44, s79
	ds_write_b16_d16_hi v238, v44 offset:2560
	v_bfe_u32 v44, v47, 16, 1
	v_add3_u32 v44, v47, v44, s79
	ds_write_b16_d16_hi v238, v44 offset:2816
	v_bfe_u32 v44, v40, 16, 1
	v_add3_u32 v40, v40, v44, s79
	ds_write_b16_d16_hi v238, v40 offset:2080
	v_bfe_u32 v40, v41, 16, 1
	v_add3_u32 v40, v41, v40, s79
	ds_write_b16_d16_hi v238, v40 offset:2336
	v_bfe_u32 v40, v42, 16, 1
	v_add3_u32 v40, v42, v40, s79
	ds_write_b16_d16_hi v238, v40 offset:2592
	v_bfe_u32 v40, v43, 16, 1
	v_add3_u32 v40, v43, v40, s79
	ds_write_b16_d16_hi v238, v40 offset:2848
	v_bfe_u32 v40, v36, 16, 1
	v_add3_u32 v36, v36, v40, s79
	ds_write_b16_d16_hi v238, v36 offset:2112
	v_bfe_u32 v36, v37, 16, 1
	v_add3_u32 v36, v37, v36, s79
	ds_write_b16_d16_hi v238, v36 offset:2368
	v_bfe_u32 v36, v38, 16, 1
	v_add3_u32 v36, v38, v36, s79
	ds_write_b16_d16_hi v238, v36 offset:2624
	v_bfe_u32 v36, v39, 16, 1
	v_add3_u32 v36, v39, v36, s79
	ds_write_b16_d16_hi v238, v36 offset:2880
	v_bfe_u32 v36, v32, 16, 1
	v_add3_u32 v32, v32, v36, s79
	ds_write_b16_d16_hi v238, v32 offset:2144
	v_bfe_u32 v32, v33, 16, 1
	v_add3_u32 v32, v33, v32, s79
	ds_write_b16_d16_hi v238, v32 offset:2400
	v_bfe_u32 v32, v34, 16, 1
	v_add3_u32 v32, v34, v32, s79
	ds_write_b16_d16_hi v238, v32 offset:2656
	v_bfe_u32 v32, v35, 16, 1
	v_add3_u32 v32, v35, v32, s79
	ds_write_b16_d16_hi v238, v32 offset:2912
	v_bfe_u32 v32, v28, 16, 1
	v_add3_u32 v28, v28, v32, s79
	ds_write_b16_d16_hi v238, v28 offset:2176
	v_bfe_u32 v28, v29, 16, 1
	v_add3_u32 v28, v29, v28, s79
	ds_write_b16_d16_hi v238, v28 offset:2432
	v_bfe_u32 v28, v30, 16, 1
	v_add3_u32 v28, v30, v28, s79
	ds_write_b16_d16_hi v238, v28 offset:2688
	v_bfe_u32 v28, v31, 16, 1
	v_add3_u32 v28, v31, v28, s79
	ds_write_b16_d16_hi v238, v28 offset:2944
	v_bfe_u32 v28, v24, 16, 1
	v_add3_u32 v24, v24, v28, s79
	ds_write_b16_d16_hi v238, v24 offset:2208
	v_bfe_u32 v24, v25, 16, 1
	v_add3_u32 v24, v25, v24, s79
	ds_write_b16_d16_hi v238, v24 offset:2464
	v_bfe_u32 v24, v26, 16, 1
	v_add3_u32 v24, v26, v24, s79
	ds_write_b16_d16_hi v238, v24 offset:2720
	v_bfe_u32 v24, v27, 16, 1
	v_add3_u32 v24, v27, v24, s79
	ds_write_b16_d16_hi v238, v24 offset:2976
	v_bfe_u32 v24, v20, 16, 1
	v_add3_u32 v20, v20, v24, s79
	ds_write_b16_d16_hi v238, v20 offset:2240
	v_bfe_u32 v20, v21, 16, 1
	v_add3_u32 v20, v21, v20, s79
	ds_write_b16_d16_hi v238, v20 offset:2496
	v_bfe_u32 v20, v22, 16, 1
	v_add3_u32 v20, v22, v20, s79
	ds_write_b16_d16_hi v238, v20 offset:2752
	v_bfe_u32 v20, v23, 16, 1
	v_add3_u32 v20, v23, v20, s79
	ds_write_b16_d16_hi v238, v20 offset:3008
	v_bfe_u32 v20, v16, 16, 1
	v_add3_u32 v16, v16, v20, s79
	ds_write_b16_d16_hi v238, v16 offset:2272
	v_bfe_u32 v16, v17, 16, 1
	v_add3_u32 v16, v17, v16, s79
	ds_write_b16_d16_hi v238, v16 offset:2528
	v_bfe_u32 v16, v18, 16, 1
	v_add3_u32 v16, v18, v16, s79
	ds_write_b16_d16_hi v238, v16 offset:2784
	v_bfe_u32 v16, v19, 16, 1
	v_add3_u32 v16, v19, v16, s79
	ds_write_b16_d16_hi v238, v16 offset:3040
	s_branch .LBB0_2273
